# v108 plus K-loop LDS-DMA addressing in saddr form (SGPR base + 32-bit VGPR offset) replacing 8 of 16 per-iteration 64-bit VALU address adds in all six GEMM loops
# speedup vs baseline: 1.0049x; 1.0049x over previous
; #define PG8_STAGE(bufoff, gbase, voff) do { _Pragma("unroll") for (int _i = 0; _i < 2; ++_i) \
;         __builtin_amdgcn_global_load_lds((const unsigned*)((const char*)(gbase) + (voff)[_i]), (PG8_LAS unsigned*)(lds + (bufoff) + ldsw + _i * 8192), 16, 0, 0); } while (0)
; #define PG8_LDA(dst, b, h) do { _Pragma("unroll") for (int m = 0; m < 4; ++m) _Pragma("unroll") for (int k = 0; k < 2; ++k) dst[m][k] = *(const PG8_LAS bf16x8*)(lds + PG8_SA(b, h) + aoff + m * 2048 + k * 1024); } while (0)
; #define PG8_LDB(dst, b, h) do { _Pragma("unroll") for (int n = 0; n < 2; ++n) _Pragma("unroll") for (int k = 0; k < 2; ++k) dst[n][k] = *(const PG8_LAS bf16x8*)(lds + PG8_SB(b, h) + boff + n * 2048 + k * 1024); } while (0)
; template <class Epi, class Sched, bool ALIGN_EPI = false, bool SP2 = false>
; __device__ __forceinline__ void gemm_phase(PG8_LAS unsigned char* lds, const Gemm g, const Sched& S, const Epi& E) {
;     ...
;         for (int t = 0; t < nt; t += 2) {
;             const bool last = (t == nt - 2);
;             const char* a1 = cA + (size_t)(t + 1) * kstep;
;             const char* a2 = last ? nA : cA + (size_t)(t + 2) * kstep; const char* b2 = last ? nB : cB + (size_t)(t + 2) * kstep;
;             const char* a3 = a2 + kstep; const char* b3 = b2 + kstep;
;             if (last && has_next) S.a_ready(nxt);
;             if constexpr (SP2) {
;             PG8_LDB(B0, 0, 0); PG8_LDB(B1, 0, 1); PG8_SCHED; PG8_LDA(At, 0, 0); PG8_STAGE(PG8_SA(1, 1), a1 + hstep, voffA);
;             PG8_WAIT_V(8); PG8_WAIT_L(0); PG8_BAR; PG8_MMA(0, 0, At, B0); PG8_MMA(0, 1, At, B1); PG8_BAR; PG8_SCHED;
;             PG8_LDA(At, 0, 1); PG8_STAGE(PG8_SB(0, 0), b2, voffB); PG8_STAGE(PG8_SB(0, 1), b2 + hstep, voffB); PG8_STAGE(PG8_SA(0, 0), a2, voffA);
;             PG8_WAIT_V(8); PG8_WAIT_L(0); PG8_BAR; PG8_MMA(1, 0, At, B0); PG8_MMA(1, 1, At, B1); PG8_BAR; PG8_SCHED;
;             PG8_LDB(B0, 1, 0); PG8_LDB(B1, 1, 1); PG8_SCHED; PG8_LDA(At, 1, 0); PG8_STAGE(PG8_SA(0, 1), a2 + hstep, voffA);
;             PG8_WAIT_V(8); PG8_WAIT_L(0); PG8_BAR; PG8_MMA(0, 0, At, B0); PG8_MMA(0, 1, At, B1); PG8_BAR; PG8_SCHED;
;             PG8_LDA(At, 1, 1); PG8_STAGE(PG8_SB(1, 0), b3, voffB); PG8_STAGE(PG8_SB(1, 1), b3 + hstep, voffB); PG8_STAGE(PG8_SA(1, 0), a3, voffA);
;             PG8_WAIT_V(8); PG8_WAIT_L(0); PG8_BAR; PG8_MMA(1, 0, At, B0); PG8_MMA(1, 1, At, B1); PG8_BAR; PG8_SCHED;
.LBB0_102:
	ds_read_b128 v[160:163], v155
	ds_read_b128 v[164:167], v155 offset:1024
	ds_read_b128 v[168:171], v155 offset:2048
	ds_read_b128 v[172:175], v155 offset:3072
	ds_read_b128 v[176:179], v157
	ds_read_b128 v[180:183], v157 offset:1024
	ds_read_b128 v[184:187], v157 offset:2048
	ds_read_b128 v[188:191], v157 offset:3072
	s_add_u32 s62, s74, 0xfff80080
	s_addc_u32 s63, s75, -1
	s_cmp_eq_u32 s90, 28
	s_cselect_b32 s79, s10, s63
	s_cselect_b32 s78, s11, s62
	s_cselect_b32 s77, s51, s89
	s_cselect_b32 s76, s55, s88
	s_add_i32 m0, s61, 0xc000
	ds_read_b128 v[192:195], v159
	ds_read_b128 v[196:199], v159 offset:1024
	ds_read_b128 v[200:203], v159 offset:2048
	ds_read_b128 v[204:207], v159 offset:3072
	ds_read_b128 v[208:211], v159 offset:4096
	ds_read_b128 v[212:215], v159 offset:5120
	ds_read_b128 v[216:219], v159 offset:6144
	ds_read_b128 v[220:223], v159 offset:7168
	global_load_lds_dwordx4 v138, s[74:75]
	s_add_i32 m0, s61, 0xe000
	s_nop 0
	global_load_lds_dwordx4 v140, s[74:75]
	s_waitcnt vmcnt(8)
	s_waitcnt lgkmcnt(0)
	s_setprio 1
	s_barrier
	v_mfma_f32_16x16x32_bf16 v[124:127], v[160:163], v[192:195], v[124:127]
	v_mfma_f32_16x16x32_bf16 v[124:127], v[164:167], v[196:199], v[124:127]
	v_mfma_f32_16x16x32_bf16 v[108:111], v[160:163], v[200:203], v[108:111]
	v_mfma_f32_16x16x32_bf16 v[108:111], v[164:167], v[204:207], v[108:111]
	v_mfma_f32_16x16x32_bf16 v[92:95], v[160:163], v[208:211], v[92:95]
	v_mfma_f32_16x16x32_bf16 v[92:95], v[164:167], v[212:215], v[92:95]
	v_mfma_f32_16x16x32_bf16 v[76:79], v[160:163], v[216:219], v[76:79]
	v_mfma_f32_16x16x32_bf16 v[76:79], v[164:167], v[220:223], v[76:79]
	v_mfma_f32_16x16x32_bf16 v[72:75], v[168:171], v[216:219], v[72:75]
	v_mfma_f32_16x16x32_bf16 v[72:75], v[172:175], v[220:223], v[72:75]
	v_mfma_f32_16x16x32_bf16 v[88:91], v[168:171], v[208:211], v[88:91]
	v_mfma_f32_16x16x32_bf16 v[88:91], v[172:175], v[212:215], v[88:91]
	v_mfma_f32_16x16x32_bf16 v[104:107], v[168:171], v[200:203], v[104:107]
	v_mfma_f32_16x16x32_bf16 v[104:107], v[172:175], v[204:207], v[104:107]
	v_mfma_f32_16x16x32_bf16 v[120:123], v[168:171], v[192:195], v[120:123]
	v_mfma_f32_16x16x32_bf16 v[120:123], v[172:175], v[196:199], v[120:123]
	v_mfma_f32_16x16x32_bf16 v[116:119], v[176:179], v[192:195], v[116:119]
	v_mfma_f32_16x16x32_bf16 v[116:119], v[180:183], v[196:199], v[116:119]
	v_mfma_f32_16x16x32_bf16 v[100:103], v[176:179], v[200:203], v[100:103]
	v_mfma_f32_16x16x32_bf16 v[100:103], v[180:183], v[204:207], v[100:103]
	v_mfma_f32_16x16x32_bf16 v[84:87], v[176:179], v[208:211], v[84:87]
	v_mfma_f32_16x16x32_bf16 v[84:87], v[180:183], v[212:215], v[84:87]
	v_mfma_f32_16x16x32_bf16 v[68:71], v[176:179], v[216:219], v[68:71]
	v_mfma_f32_16x16x32_bf16 v[68:71], v[180:183], v[220:223], v[68:71]
	v_mfma_f32_16x16x32_bf16 v[64:67], v[184:187], v[216:219], v[64:67]
	v_mfma_f32_16x16x32_bf16 v[64:67], v[188:191], v[220:223], v[64:67]
	v_mfma_f32_16x16x32_bf16 v[80:83], v[184:187], v[208:211], v[80:83]
	v_mfma_f32_16x16x32_bf16 v[80:83], v[188:191], v[212:215], v[80:83]
	s_setprio 2
	s_barrier
	v_mfma_f32_16x16x32_bf16 v[96:99], v[184:187], v[200:203], v[96:99]
	v_mfma_f32_16x16x32_bf16 v[96:99], v[188:191], v[204:207], v[96:99]
	v_mfma_f32_16x16x32_bf16 v[112:115], v[184:187], v[192:195], v[112:115]
	v_mfma_f32_16x16x32_bf16 v[112:115], v[188:191], v[196:199], v[112:115]
	s_setprio 0
	s_add_i32 s62, s84, s35
	v_lshl_add_u64 v[224:225], s[76:77], 0, v[130:131]
	s_mov_b32 m0, s62
	ds_read_b128 v[192:195], v159 offset:16384
	ds_read_b128 v[196:199], v159 offset:17408
	ds_read_b128 v[200:203], v159 offset:18432
	ds_read_b128 v[204:207], v159 offset:19456
	ds_read_b128 v[208:211], v159 offset:20480
	ds_read_b128 v[212:215], v159 offset:21504
	ds_read_b128 v[216:219], v159 offset:22528
	ds_read_b128 v[220:223], v159 offset:23552
	global_load_lds_dwordx4 v130, s[76:77]
	s_add_i32 m0, s62, 0x2000
	s_add_u32 s92, s76, 0x80000
	v_lshl_add_u64 v[226:227], s[76:77], 0, v[134:135]
	s_addc_u32 s93, s77, 0
	s_add_i32 s62, s85, s35
	global_load_lds_dwordx4 v134, s[76:77]
	s_mov_b32 m0, s62
	v_lshl_add_u64 v[230:231], s[78:79], 0, v[132:133]
	global_load_lds_dwordx4 v130, s[92:93]
	s_add_i32 m0, s62, 0x2000
	s_nop 0
	global_load_lds_dwordx4 v134, s[92:93]
	v_lshl_add_u64 v[228:229], s[78:79], 0, v[128:129]
	s_mov_b32 m0, s61
	s_nop 0
	global_load_lds_dwordx4 v128, s[78:79]
	s_mov_b32 m0, s65
	s_nop 0
	global_load_lds_dwordx4 v132, s[78:79]
	s_waitcnt vmcnt(8)
	s_waitcnt lgkmcnt(0)
	s_setprio 1
	s_barrier
	v_mfma_f32_16x16x32_bf16 v[60:63], v[160:163], v[192:195], v[60:63]
	v_mfma_f32_16x16x32_bf16 v[60:63], v[164:167], v[196:199], v[60:63]
	v_mfma_f32_16x16x32_bf16 v[44:47], v[160:163], v[200:203], v[44:47]
	v_mfma_f32_16x16x32_bf16 v[44:47], v[164:167], v[204:207], v[44:47]
	v_mfma_f32_16x16x32_bf16 v[28:31], v[160:163], v[208:211], v[28:31]
	v_mfma_f32_16x16x32_bf16 v[28:31], v[164:167], v[212:215], v[28:31]
	v_mfma_f32_16x16x32_bf16 v[12:15], v[160:163], v[216:219], v[12:15]
	v_mfma_f32_16x16x32_bf16 v[12:15], v[164:167], v[220:223], v[12:15]
	v_mfma_f32_16x16x32_bf16 v[8:11], v[168:171], v[216:219], v[8:11]
	v_mfma_f32_16x16x32_bf16 v[8:11], v[172:175], v[220:223], v[8:11]
	v_mfma_f32_16x16x32_bf16 v[24:27], v[168:171], v[208:211], v[24:27]
	v_mfma_f32_16x16x32_bf16 v[24:27], v[172:175], v[212:215], v[24:27]
	v_mfma_f32_16x16x32_bf16 v[40:43], v[168:171], v[200:203], v[40:43]
	v_mfma_f32_16x16x32_bf16 v[40:43], v[172:175], v[204:207], v[40:43]
	v_mfma_f32_16x16x32_bf16 v[56:59], v[168:171], v[192:195], v[56:59]
	v_mfma_f32_16x16x32_bf16 v[56:59], v[172:175], v[196:199], v[56:59]
	v_mfma_f32_16x16x32_bf16 v[52:55], v[176:179], v[192:195], v[52:55]
	v_mfma_f32_16x16x32_bf16 v[52:55], v[180:183], v[196:199], v[52:55]
	v_mfma_f32_16x16x32_bf16 v[36:39], v[176:179], v[200:203], v[36:39]
	v_mfma_f32_16x16x32_bf16 v[36:39], v[180:183], v[204:207], v[36:39]
	v_mfma_f32_16x16x32_bf16 v[20:23], v[176:179], v[208:211], v[20:23]
	v_mfma_f32_16x16x32_bf16 v[20:23], v[180:183], v[212:215], v[20:23]
	v_mfma_f32_16x16x32_bf16 v[4:7], v[176:179], v[216:219], v[4:7]
	v_mfma_f32_16x16x32_bf16 v[4:7], v[180:183], v[220:223], v[4:7]
	v_mfma_f32_16x16x32_bf16 v[0:3], v[184:187], v[216:219], v[0:3]
	v_mfma_f32_16x16x32_bf16 v[0:3], v[188:191], v[220:223], v[0:3]
	v_mfma_f32_16x16x32_bf16 v[16:19], v[184:187], v[208:211], v[16:19]
	v_mfma_f32_16x16x32_bf16 v[16:19], v[188:191], v[212:215], v[16:19]
	s_setprio 2
	s_barrier
; #define PG8_STAGE(bufoff, gbase, voff) do { _Pragma("unroll") for (int _i = 0; _i < 2; ++_i) \
;         __builtin_amdgcn_global_load_lds((const unsigned*)((const char*)(gbase) + (voff)[_i]), (PG8_LAS unsigned*)(lds + (bufoff) + ldsw + _i * 8192), 16, 0, 0); } while (0)
; #define PG8_LDA(dst, b, h) do { _Pragma("unroll") for (int m = 0; m < 4; ++m) _Pragma("unroll") for (int k = 0; k < 2; ++k) dst[m][k] = *(const PG8_LAS bf16x8*)(lds + PG8_SA(b, h) + aoff + m * 2048 + k * 1024); } while (0)
; #define PG8_LDB(dst, b, h) do { _Pragma("unroll") for (int n = 0; n < 2; ++n) _Pragma("unroll") for (int k = 0; k < 2; ++k) dst[n][k] = *(const PG8_LAS bf16x8*)(lds + PG8_SB(b, h) + boff + n * 2048 + k * 1024); } while (0)
; #define PG8_MMA(ai, bj, At, Bt) do { __builtin_amdgcn_s_setprio(1); _Pragma("unroll") for (int m = 0; m < 4; ++m) _Pragma("unroll") for (int n = 0; n < 2; ++n) _Pragma("unroll") for (int k = 0; k < 2; ++k) \
;         acc[ai][bj][m][n] = __builtin_amdgcn_mfma_f32_16x16x32_bf16(Bt[n][k], At[m][k], acc[ai][bj][m][n], 0, 0, 0); __builtin_amdgcn_s_setprio(0); } while (0)
; #define PG8_WAIT_V(n) asm volatile("s_waitcnt vmcnt(" #n ")" ::: "memory")
; template <class Epi, class Sched, bool ALIGN_EPI = false, bool SP2 = false>
; __device__ __forceinline__ void gemm_phase(PG8_LAS unsigned char* lds, const Gemm g, const Sched& S, const Epi& E) {
;     ...
;             PG8_LDB(B0, 0, 0); PG8_LDB(B1, 0, 1); PG8_SCHED; PG8_LDA(At, 0, 0); PG8_STAGE(PG8_SA(1, 1), a1 + hstep, voffA);
;             PG8_WAIT_V(8); PG8_WAIT_L(0); PG8_BAR; PG8_MMA(0, 0, At, B0); PG8_MMA(0, 1, At, B1); PG8_BAR; PG8_SCHED;
;             PG8_LDA(At, 0, 1); PG8_STAGE(PG8_SB(0, 0), b2, voffB); PG8_STAGE(PG8_SB(0, 1), b2 + hstep, voffB); PG8_STAGE(PG8_SA(0, 0), a2, voffA);
;             PG8_WAIT_V(8); PG8_WAIT_L(0); PG8_BAR; PG8_MMA(1, 0, At, B0); PG8_MMA(1, 1, At, B1); PG8_BAR; PG8_SCHED;
;             PG8_LDB(B0, 1, 0); PG8_LDB(B1, 1, 1); PG8_SCHED; PG8_LDA(At, 1, 0); PG8_STAGE(PG8_SA(0, 1), a2 + hstep, voffA);
;             PG8_WAIT_V(8); PG8_WAIT_L(0); PG8_BAR; PG8_MMA(0, 0, At, B0); PG8_MMA(0, 1, At, B1); PG8_BAR; PG8_SCHED;
;             PG8_LDA(At, 1, 1); PG8_STAGE(PG8_SB(1, 0), b3, voffB); PG8_STAGE(PG8_SB(1, 1), b3 + hstep, voffB); PG8_STAGE(PG8_SA(1, 0), a3, voffA);
;             PG8_WAIT_V(8); PG8_WAIT_L(0); PG8_BAR; PG8_MMA(1, 0, At, B0); PG8_MMA(1, 1, At, B1); PG8_BAR; PG8_SCHED;
	v_mfma_f32_16x16x32_bf16 v[32:35], v[184:187], v[200:203], v[32:35]
	v_mfma_f32_16x16x32_bf16 v[32:35], v[188:191], v[204:207], v[32:35]
	v_mfma_f32_16x16x32_bf16 v[48:51], v[184:187], v[192:195], v[48:51]
	v_mfma_f32_16x16x32_bf16 v[48:51], v[188:191], v[196:199], v[48:51]
	s_setprio 0
	s_add_i32 s62, 0, 0x18000
	s_add_i32 s63, 0, 0x1c000
	v_add_u32_e32 v172, s62, v147
	v_add_u32_e32 v188, s63, v147
	ds_read_b128 v[160:163], v172
	ds_read_b128 v[164:167], v172 offset:1024
	ds_read_b128 v[168:171], v172 offset:2048
	ds_read_b128 v[172:175], v172 offset:3072
	ds_read_b128 v[176:179], v188
	ds_read_b128 v[180:183], v188 offset:1024
	ds_read_b128 v[184:187], v188 offset:2048
	ds_read_b128 v[188:191], v188 offset:3072
	s_add_u32 s78, s78, 0x80000
	s_addc_u32 s79, s79, 0
	s_mov_b32 m0, s66
	ds_read_b128 v[192:195], v159 offset:32768
	ds_read_b128 v[196:199], v159 offset:33792
	ds_read_b128 v[200:203], v159 offset:34816
	ds_read_b128 v[204:207], v159 offset:35840
	ds_read_b128 v[208:211], v159 offset:36864
	ds_read_b128 v[212:215], v159 offset:37888
	ds_read_b128 v[216:219], v159 offset:38912
	ds_read_b128 v[220:223], v159 offset:39936
	global_load_lds_dwordx4 v128, s[78:79]
	s_mov_b32 m0, s67
	s_nop 0
	global_load_lds_dwordx4 v132, s[78:79]
	s_waitcnt vmcnt(8)
	s_waitcnt lgkmcnt(0)
	s_setprio 1
	s_barrier
	v_mfma_f32_16x16x32_bf16 v[124:127], v[160:163], v[192:195], v[124:127]
	v_mfma_f32_16x16x32_bf16 v[124:127], v[164:167], v[196:199], v[124:127]
	v_mfma_f32_16x16x32_bf16 v[108:111], v[160:163], v[200:203], v[108:111]
	v_mfma_f32_16x16x32_bf16 v[108:111], v[164:167], v[204:207], v[108:111]
	v_mfma_f32_16x16x32_bf16 v[92:95], v[160:163], v[208:211], v[92:95]
	v_mfma_f32_16x16x32_bf16 v[92:95], v[164:167], v[212:215], v[92:95]
	v_mfma_f32_16x16x32_bf16 v[76:79], v[160:163], v[216:219], v[76:79]
	v_mfma_f32_16x16x32_bf16 v[76:79], v[164:167], v[220:223], v[76:79]
	v_mfma_f32_16x16x32_bf16 v[72:75], v[168:171], v[216:219], v[72:75]
	v_mfma_f32_16x16x32_bf16 v[72:75], v[172:175], v[220:223], v[72:75]
	v_mfma_f32_16x16x32_bf16 v[88:91], v[168:171], v[208:211], v[88:91]
	v_mfma_f32_16x16x32_bf16 v[88:91], v[172:175], v[212:215], v[88:91]
	v_mfma_f32_16x16x32_bf16 v[104:107], v[168:171], v[200:203], v[104:107]
	v_mfma_f32_16x16x32_bf16 v[104:107], v[172:175], v[204:207], v[104:107]
	v_mfma_f32_16x16x32_bf16 v[120:123], v[168:171], v[192:195], v[120:123]
	v_mfma_f32_16x16x32_bf16 v[120:123], v[172:175], v[196:199], v[120:123]
	v_mfma_f32_16x16x32_bf16 v[116:119], v[176:179], v[192:195], v[116:119]
	v_mfma_f32_16x16x32_bf16 v[116:119], v[180:183], v[196:199], v[116:119]
	v_mfma_f32_16x16x32_bf16 v[100:103], v[176:179], v[200:203], v[100:103]
	v_mfma_f32_16x16x32_bf16 v[100:103], v[180:183], v[204:207], v[100:103]
	v_mfma_f32_16x16x32_bf16 v[84:87], v[176:179], v[208:211], v[84:87]
	v_mfma_f32_16x16x32_bf16 v[84:87], v[180:183], v[212:215], v[84:87]
	v_mfma_f32_16x16x32_bf16 v[68:71], v[176:179], v[216:219], v[68:71]
	v_mfma_f32_16x16x32_bf16 v[68:71], v[180:183], v[220:223], v[68:71]
	v_mfma_f32_16x16x32_bf16 v[64:67], v[184:187], v[216:219], v[64:67]
	v_mfma_f32_16x16x32_bf16 v[64:67], v[188:191], v[220:223], v[64:67]
	v_mfma_f32_16x16x32_bf16 v[80:83], v[184:187], v[208:211], v[80:83]
	v_mfma_f32_16x16x32_bf16 v[80:83], v[188:191], v[212:215], v[80:83]
	s_setprio 2
	s_barrier
; #define PG8_STAGE(bufoff, gbase, voff) do { _Pragma("unroll") for (int _i = 0; _i < 2; ++_i) \
;         __builtin_amdgcn_global_load_lds((const unsigned*)((const char*)(gbase) + (voff)[_i]), (PG8_LAS unsigned*)(lds + (bufoff) + ldsw + _i * 8192), 16, 0, 0); } while (0)
; #define PG8_LDA(dst, b, h) do { _Pragma("unroll") for (int m = 0; m < 4; ++m) _Pragma("unroll") for (int k = 0; k < 2; ++k) dst[m][k] = *(const PG8_LAS bf16x8*)(lds + PG8_SA(b, h) + aoff + m * 2048 + k * 1024); } while (0)
; #define PG8_LDB(dst, b, h) do { _Pragma("unroll") for (int n = 0; n < 2; ++n) _Pragma("unroll") for (int k = 0; k < 2; ++k) dst[n][k] = *(const PG8_LAS bf16x8*)(lds + PG8_SB(b, h) + boff + n * 2048 + k * 1024); } while (0)
; #define PG8_MMA(ai, bj, At, Bt) do { __builtin_amdgcn_s_setprio(1); _Pragma("unroll") for (int m = 0; m < 4; ++m) _Pragma("unroll") for (int n = 0; n < 2; ++n) _Pragma("unroll") for (int k = 0; k < 2; ++k) \
;         acc[ai][bj][m][n] = __builtin_amdgcn_mfma_f32_16x16x32_bf16(Bt[n][k], At[m][k], acc[ai][bj][m][n], 0, 0, 0); __builtin_amdgcn_s_setprio(0); } while (0)
; #define PG8_WAIT_V(n) asm volatile("s_waitcnt vmcnt(" #n ")" ::: "memory")
; template <class Epi, class Sched, bool ALIGN_EPI = false, bool SP2 = false>
; __device__ __forceinline__ void gemm_phase(PG8_LAS unsigned char* lds, const Gemm g, const Sched& S, const Epi& E) {
;     ...
;             PG8_LDB(B0, 0, 0); PG8_LDB(B1, 0, 1); PG8_SCHED; PG8_LDA(At, 0, 0); PG8_STAGE(PG8_SA(1, 1), a1 + hstep, voffA);
;             PG8_WAIT_V(8); PG8_WAIT_L(0); PG8_BAR; PG8_MMA(0, 0, At, B0); PG8_MMA(0, 1, At, B1); PG8_BAR; PG8_SCHED;
;             PG8_LDA(At, 0, 1); PG8_STAGE(PG8_SB(0, 0), b2, voffB); PG8_STAGE(PG8_SB(0, 1), b2 + hstep, voffB); PG8_STAGE(PG8_SA(0, 0), a2, voffA);
;             PG8_WAIT_V(8); PG8_WAIT_L(0); PG8_BAR; PG8_MMA(1, 0, At, B0); PG8_MMA(1, 1, At, B1); PG8_BAR; PG8_SCHED;
;             PG8_LDB(B0, 1, 0); PG8_LDB(B1, 1, 1); PG8_SCHED; PG8_LDA(At, 1, 0); PG8_STAGE(PG8_SA(0, 1), a2 + hstep, voffA);
;             PG8_WAIT_V(8); PG8_WAIT_L(0); PG8_BAR; PG8_MMA(0, 0, At, B0); PG8_MMA(0, 1, At, B1); PG8_BAR; PG8_SCHED;
;             PG8_LDA(At, 1, 1); PG8_STAGE(PG8_SB(1, 0), b3, voffB); PG8_STAGE(PG8_SB(1, 1), b3 + hstep, voffB); PG8_STAGE(PG8_SA(1, 0), a3, voffA);
;             PG8_WAIT_V(8); PG8_WAIT_L(0); PG8_BAR; PG8_MMA(1, 0, At, B0); PG8_MMA(1, 1, At, B1); PG8_BAR; PG8_SCHED;
	v_mfma_f32_16x16x32_bf16 v[96:99], v[184:187], v[200:203], v[96:99]
	v_mfma_f32_16x16x32_bf16 v[96:99], v[188:191], v[204:207], v[96:99]
	v_mfma_f32_16x16x32_bf16 v[112:115], v[184:187], v[192:195], v[112:115]
	v_mfma_f32_16x16x32_bf16 v[112:115], v[188:191], v[196:199], v[112:115]
	s_setprio 0
	s_add_i32 s62, s62, s35
	v_lshl_add_u64 v[224:225], v[224:225], 0, s[18:19]
	s_mov_b32 m0, s62
	ds_read_b128 v[192:195], v159 offset:49152
	ds_read_b128 v[196:199], v159 offset:50176
	ds_read_b128 v[200:203], v159 offset:51200
	ds_read_b128 v[204:207], v159 offset:52224
	ds_read_b128 v[208:211], v159 offset:53248
	ds_read_b128 v[212:215], v159 offset:54272
	ds_read_b128 v[216:219], v159 offset:55296
	ds_read_b128 v[220:223], v159 offset:56320
	global_load_lds_dwordx4 v[224:225], off
	s_add_i32 m0, s62, 0x2000
	s_add_u32 s76, s76, 0x80080
	v_lshl_add_u64 v[224:225], v[226:227], 0, s[18:19]
	s_addc_u32 s77, s77, 0
	s_add_i32 s62, s63, s35
	global_load_lds_dwordx4 v[224:225], off
	s_mov_b32 m0, s62
	s_nop 0
	global_load_lds_dwordx4 v130, s[76:77]
	s_add_i32 m0, s62, 0x2000
	s_nop 0
	global_load_lds_dwordx4 v134, s[76:77]
	v_lshl_add_u64 v[224:225], v[228:229], 0, s[18:19]
	s_mov_b32 m0, s81
	s_nop 0
	global_load_lds_dwordx4 v[224:225], off
	v_lshl_add_u64 v[224:225], v[230:231], 0, s[18:19]
	s_mov_b32 m0, s82
	s_nop 0
	global_load_lds_dwordx4 v[224:225], off
	s_waitcnt vmcnt(8)
	s_waitcnt lgkmcnt(0)
	s_setprio 1
	s_barrier
	v_mfma_f32_16x16x32_bf16 v[60:63], v[160:163], v[192:195], v[60:63]
	v_mfma_f32_16x16x32_bf16 v[60:63], v[164:167], v[196:199], v[60:63]
	v_mfma_f32_16x16x32_bf16 v[44:47], v[160:163], v[200:203], v[44:47]
	v_mfma_f32_16x16x32_bf16 v[44:47], v[164:167], v[204:207], v[44:47]
	v_mfma_f32_16x16x32_bf16 v[28:31], v[160:163], v[208:211], v[28:31]
	v_mfma_f32_16x16x32_bf16 v[28:31], v[164:167], v[212:215], v[28:31]
	v_mfma_f32_16x16x32_bf16 v[12:15], v[160:163], v[216:219], v[12:15]
	v_mfma_f32_16x16x32_bf16 v[12:15], v[164:167], v[220:223], v[12:15]
	v_mfma_f32_16x16x32_bf16 v[8:11], v[168:171], v[216:219], v[8:11]
	v_mfma_f32_16x16x32_bf16 v[8:11], v[172:175], v[220:223], v[8:11]
	v_mfma_f32_16x16x32_bf16 v[24:27], v[168:171], v[208:211], v[24:27]
	v_mfma_f32_16x16x32_bf16 v[24:27], v[172:175], v[212:215], v[24:27]
	v_mfma_f32_16x16x32_bf16 v[40:43], v[168:171], v[200:203], v[40:43]
	v_mfma_f32_16x16x32_bf16 v[40:43], v[172:175], v[204:207], v[40:43]
	v_mfma_f32_16x16x32_bf16 v[56:59], v[168:171], v[192:195], v[56:59]
	v_mfma_f32_16x16x32_bf16 v[56:59], v[172:175], v[196:199], v[56:59]
	v_mfma_f32_16x16x32_bf16 v[52:55], v[176:179], v[192:195], v[52:55]
	v_mfma_f32_16x16x32_bf16 v[52:55], v[180:183], v[196:199], v[52:55]
	v_mfma_f32_16x16x32_bf16 v[36:39], v[176:179], v[200:203], v[36:39]
	v_mfma_f32_16x16x32_bf16 v[36:39], v[180:183], v[204:207], v[36:39]
	v_mfma_f32_16x16x32_bf16 v[20:23], v[176:179], v[208:211], v[20:23]
	v_mfma_f32_16x16x32_bf16 v[20:23], v[180:183], v[212:215], v[20:23]
	v_mfma_f32_16x16x32_bf16 v[4:7], v[176:179], v[216:219], v[4:7]
	v_mfma_f32_16x16x32_bf16 v[4:7], v[180:183], v[220:223], v[4:7]
	v_mfma_f32_16x16x32_bf16 v[0:3], v[184:187], v[216:219], v[0:3]
	v_mfma_f32_16x16x32_bf16 v[0:3], v[188:191], v[220:223], v[0:3]
	v_mfma_f32_16x16x32_bf16 v[16:19], v[184:187], v[208:211], v[16:19]
	v_mfma_f32_16x16x32_bf16 v[16:19], v[188:191], v[212:215], v[16:19]
	s_setprio 2
	s_barrier
	v_mfma_f32_16x16x32_bf16 v[32:35], v[184:187], v[200:203], v[32:35]
	v_mfma_f32_16x16x32_bf16 v[32:35], v[188:191], v[204:207], v[32:35]
	v_mfma_f32_16x16x32_bf16 v[48:51], v[184:187], v[192:195], v[48:51]
	v_mfma_f32_16x16x32_bf16 v[48:51], v[188:191], v[196:199], v[48:51]
	s_setprio 0
	s_add_i32 s90, s90, 2
	s_add_u32 s74, s74, 0x100
	s_addc_u32 s75, s75, 0
	s_add_u32 s88, s88, 0x100
	s_addc_u32 s89, s89, 0
	s_cmp_gt_u32 s90, 29
	s_cbranch_scc0 .LBB0_102
	s_and_b64 vcc, exec, s[22:23]
	s_cbranch_vccz .LBB0_105
	s_barrier

; #define PG8_STAGE(bufoff, gbase, voff) do { _Pragma("unroll") for (int _i = 0; _i < 2; ++_i) \
;         __builtin_amdgcn_global_load_lds((const unsigned*)((const char*)(gbase) + (voff)[_i]), (PG8_LAS unsigned*)(lds + (bufoff) + ldsw + _i * 8192), 16, 0, 0); } while (0)
; #define PG8_LDA(dst, b, h) do { _Pragma("unroll") for (int m = 0; m < 4; ++m) _Pragma("unroll") for (int k = 0; k < 2; ++k) dst[m][k] = *(const PG8_LAS bf16x8*)(lds + PG8_SA(b, h) + aoff + m * 2048 + k * 1024); } while (0)
; #define PG8_LDB(dst, b, h) do { _Pragma("unroll") for (int n = 0; n < 2; ++n) _Pragma("unroll") for (int k = 0; k < 2; ++k) dst[n][k] = *(const PG8_LAS bf16x8*)(lds + PG8_SB(b, h) + boff + n * 2048 + k * 1024); } while (0)
; template <class Epi, class Sched, bool ALIGN_EPI = false, bool SP2 = false>
; __device__ __forceinline__ void gemm_phase(PG8_LAS unsigned char* lds, const Gemm g, const Sched& S, const Epi& E) {
;     ...
;         for (int t = 0; t < nt; t += 2) {
;             const bool last = (t == nt - 2);
;             const char* a1 = cA + (size_t)(t + 1) * kstep;
;             const char* a2 = last ? nA : cA + (size_t)(t + 2) * kstep; const char* b2 = last ? nB : cB + (size_t)(t + 2) * kstep;
;             const char* a3 = a2 + kstep; const char* b3 = b2 + kstep;
;             if (last && has_next) S.a_ready(nxt);
;             if constexpr (SP2) {
;             PG8_LDB(B0, 0, 0); PG8_LDB(B1, 0, 1); PG8_SCHED; PG8_LDA(At, 0, 0); PG8_STAGE(PG8_SA(1, 1), a1 + hstep, voffA);
;             PG8_WAIT_V(8); PG8_WAIT_L(0); PG8_BAR; PG8_MMA(0, 0, At, B0); PG8_MMA(0, 1, At, B1); PG8_BAR; PG8_SCHED;
;             PG8_LDA(At, 0, 1); PG8_STAGE(PG8_SB(0, 0), b2, voffB); PG8_STAGE(PG8_SB(0, 1), b2 + hstep, voffB); PG8_STAGE(PG8_SA(0, 0), a2, voffA);
;             PG8_WAIT_V(8); PG8_WAIT_L(0); PG8_BAR; PG8_MMA(1, 0, At, B0); PG8_MMA(1, 1, At, B1); PG8_BAR; PG8_SCHED;
;             PG8_LDB(B0, 1, 0); PG8_LDB(B1, 1, 1); PG8_SCHED; PG8_LDA(At, 1, 0); PG8_STAGE(PG8_SA(0, 1), a2 + hstep, voffA);
;             PG8_WAIT_V(8); PG8_WAIT_L(0); PG8_BAR; PG8_MMA(0, 0, At, B0); PG8_MMA(0, 1, At, B1); PG8_BAR; PG8_SCHED;
;             PG8_LDA(At, 1, 1); PG8_STAGE(PG8_SB(1, 0), b3, voffB); PG8_STAGE(PG8_SB(1, 1), b3 + hstep, voffB); PG8_STAGE(PG8_SA(1, 0), a3, voffA);
;             PG8_WAIT_V(8); PG8_WAIT_L(0); PG8_BAR; PG8_MMA(1, 0, At, B0); PG8_MMA(1, 1, At, B1); PG8_BAR; PG8_SCHED;
.LBB0_179:
	ds_read_b128 v[144:147], v155
	ds_read_b128 v[160:163], v155 offset:1024
	ds_read_b128 v[164:167], v155 offset:2048
	ds_read_b128 v[168:171], v155 offset:3072
	ds_read_b128 v[172:175], v156
	ds_read_b128 v[176:179], v156 offset:1024
	ds_read_b128 v[180:183], v156 offset:2048
	ds_read_b128 v[184:187], v156 offset:3072
	s_add_u32 s62, s76, 0xffea0080
	s_addc_u32 s63, s77, -1
	s_cmpk_eq_i32 s92, 0x54
	s_cselect_b32 s81, s7, s63
	s_cselect_b32 s80, s6, s62
	s_cselect_b32 s79, s75, s91
	s_cselect_b32 s78, s74, s50
	s_add_i32 m0, s52, 0xc000
	ds_read_b128 v[188:191], v157
	ds_read_b128 v[192:195], v157 offset:1024
	ds_read_b128 v[196:199], v157 offset:2048
	ds_read_b128 v[200:203], v157 offset:3072
	ds_read_b128 v[204:207], v157 offset:4096
	ds_read_b128 v[208:211], v157 offset:5120
	ds_read_b128 v[212:215], v157 offset:6144
	ds_read_b128 v[216:219], v157 offset:7168
	global_load_lds_dwordx4 v136, s[76:77]
	s_add_i32 m0, s52, 0xe000
	s_nop 0
	global_load_lds_dwordx4 v138, s[76:77]
	s_waitcnt vmcnt(8)
	s_waitcnt lgkmcnt(0)
	s_setprio 1
	s_barrier
	v_mfma_f32_16x16x32_bf16 v[124:127], v[144:147], v[188:191], v[124:127]
	v_mfma_f32_16x16x32_bf16 v[124:127], v[160:163], v[192:195], v[124:127]
	v_mfma_f32_16x16x32_bf16 v[108:111], v[144:147], v[196:199], v[108:111]
	v_mfma_f32_16x16x32_bf16 v[108:111], v[160:163], v[200:203], v[108:111]
	v_mfma_f32_16x16x32_bf16 v[92:95], v[144:147], v[204:207], v[92:95]
	v_mfma_f32_16x16x32_bf16 v[92:95], v[160:163], v[208:211], v[92:95]
	v_mfma_f32_16x16x32_bf16 v[76:79], v[144:147], v[212:215], v[76:79]
	v_mfma_f32_16x16x32_bf16 v[76:79], v[160:163], v[216:219], v[76:79]
	v_mfma_f32_16x16x32_bf16 v[72:75], v[164:167], v[212:215], v[72:75]
	v_mfma_f32_16x16x32_bf16 v[72:75], v[168:171], v[216:219], v[72:75]
	v_mfma_f32_16x16x32_bf16 v[88:91], v[164:167], v[204:207], v[88:91]
	v_mfma_f32_16x16x32_bf16 v[88:91], v[168:171], v[208:211], v[88:91]
	v_mfma_f32_16x16x32_bf16 v[104:107], v[164:167], v[196:199], v[104:107]
	v_mfma_f32_16x16x32_bf16 v[104:107], v[168:171], v[200:203], v[104:107]
	v_mfma_f32_16x16x32_bf16 v[120:123], v[164:167], v[188:191], v[120:123]
	v_mfma_f32_16x16x32_bf16 v[120:123], v[168:171], v[192:195], v[120:123]
	v_mfma_f32_16x16x32_bf16 v[116:119], v[172:175], v[188:191], v[116:119]
	v_mfma_f32_16x16x32_bf16 v[116:119], v[176:179], v[192:195], v[116:119]
	v_mfma_f32_16x16x32_bf16 v[100:103], v[172:175], v[196:199], v[100:103]
	v_mfma_f32_16x16x32_bf16 v[100:103], v[176:179], v[200:203], v[100:103]
	v_mfma_f32_16x16x32_bf16 v[84:87], v[172:175], v[204:207], v[84:87]
	v_mfma_f32_16x16x32_bf16 v[84:87], v[176:179], v[208:211], v[84:87]
	v_mfma_f32_16x16x32_bf16 v[68:71], v[172:175], v[212:215], v[68:71]
	v_mfma_f32_16x16x32_bf16 v[68:71], v[176:179], v[216:219], v[68:71]
	v_mfma_f32_16x16x32_bf16 v[64:67], v[180:183], v[212:215], v[64:67]
	v_mfma_f32_16x16x32_bf16 v[64:67], v[184:187], v[216:219], v[64:67]
	v_mfma_f32_16x16x32_bf16 v[80:83], v[180:183], v[204:207], v[80:83]
	v_mfma_f32_16x16x32_bf16 v[80:83], v[184:187], v[208:211], v[80:83]
	s_setprio 2
	s_barrier
	v_mfma_f32_16x16x32_bf16 v[96:99], v[180:183], v[196:199], v[96:99]
	v_mfma_f32_16x16x32_bf16 v[96:99], v[184:187], v[200:203], v[96:99]
	v_mfma_f32_16x16x32_bf16 v[112:115], v[180:183], v[188:191], v[112:115]
	v_mfma_f32_16x16x32_bf16 v[112:115], v[184:187], v[192:195], v[112:115]
	s_setprio 0
	s_add_i32 s62, s86, s35
	v_lshl_add_u64 v[220:221], s[78:79], 0, v[130:131]
	s_mov_b32 m0, s62
	ds_read_b128 v[188:191], v157 offset:16384
	ds_read_b128 v[192:195], v157 offset:17408
	ds_read_b128 v[196:199], v157 offset:18432
	ds_read_b128 v[200:203], v157 offset:19456
	ds_read_b128 v[204:207], v157 offset:20480
	ds_read_b128 v[208:211], v157 offset:21504
	ds_read_b128 v[212:215], v157 offset:22528
	ds_read_b128 v[216:219], v157 offset:23552
	global_load_lds_dwordx4 v130, s[78:79]
	s_add_i32 m0, s62, 0x2000
	s_add_u32 s94, s78, 0x160000
	v_lshl_add_u64 v[222:223], s[78:79], 0, v[134:135]
	s_addc_u32 s95, s79, 0
	s_add_i32 s62, s87, s35
	global_load_lds_dwordx4 v134, s[78:79]
	s_mov_b32 m0, s62
	v_lshl_add_u64 v[226:227], s[80:81], 0, v[132:133]
	global_load_lds_dwordx4 v130, s[94:95]
	s_add_i32 m0, s62, 0x2000
	s_nop 0
	global_load_lds_dwordx4 v134, s[94:95]
	v_lshl_add_u64 v[224:225], s[80:81], 0, v[128:129]
	s_mov_b32 m0, s52
	s_nop 0
	global_load_lds_dwordx4 v128, s[80:81]
	s_mov_b32 m0, s53
	s_nop 0
	global_load_lds_dwordx4 v132, s[80:81]
	s_waitcnt vmcnt(8)
	s_waitcnt lgkmcnt(0)
	s_setprio 1
	s_barrier
	v_mfma_f32_16x16x32_bf16 v[60:63], v[144:147], v[188:191], v[60:63]
	v_mfma_f32_16x16x32_bf16 v[60:63], v[160:163], v[192:195], v[60:63]
	v_mfma_f32_16x16x32_bf16 v[44:47], v[144:147], v[196:199], v[44:47]
	v_mfma_f32_16x16x32_bf16 v[44:47], v[160:163], v[200:203], v[44:47]
	v_mfma_f32_16x16x32_bf16 v[28:31], v[144:147], v[204:207], v[28:31]
	v_mfma_f32_16x16x32_bf16 v[28:31], v[160:163], v[208:211], v[28:31]
	v_mfma_f32_16x16x32_bf16 v[12:15], v[144:147], v[212:215], v[12:15]
	v_mfma_f32_16x16x32_bf16 v[12:15], v[160:163], v[216:219], v[12:15]
	v_mfma_f32_16x16x32_bf16 v[8:11], v[164:167], v[212:215], v[8:11]
	v_mfma_f32_16x16x32_bf16 v[8:11], v[168:171], v[216:219], v[8:11]
	v_mfma_f32_16x16x32_bf16 v[24:27], v[164:167], v[204:207], v[24:27]
	v_mfma_f32_16x16x32_bf16 v[24:27], v[168:171], v[208:211], v[24:27]
	v_mfma_f32_16x16x32_bf16 v[40:43], v[164:167], v[196:199], v[40:43]
	v_mfma_f32_16x16x32_bf16 v[40:43], v[168:171], v[200:203], v[40:43]
	v_mfma_f32_16x16x32_bf16 v[56:59], v[164:167], v[188:191], v[56:59]
	v_mfma_f32_16x16x32_bf16 v[56:59], v[168:171], v[192:195], v[56:59]
	v_mfma_f32_16x16x32_bf16 v[52:55], v[172:175], v[188:191], v[52:55]
	v_mfma_f32_16x16x32_bf16 v[52:55], v[176:179], v[192:195], v[52:55]
	v_mfma_f32_16x16x32_bf16 v[36:39], v[172:175], v[196:199], v[36:39]
	v_mfma_f32_16x16x32_bf16 v[36:39], v[176:179], v[200:203], v[36:39]
	v_mfma_f32_16x16x32_bf16 v[20:23], v[172:175], v[204:207], v[20:23]
	v_mfma_f32_16x16x32_bf16 v[20:23], v[176:179], v[208:211], v[20:23]
	v_mfma_f32_16x16x32_bf16 v[4:7], v[172:175], v[212:215], v[4:7]
	v_mfma_f32_16x16x32_bf16 v[4:7], v[176:179], v[216:219], v[4:7]
	v_mfma_f32_16x16x32_bf16 v[0:3], v[180:183], v[212:215], v[0:3]
	v_mfma_f32_16x16x32_bf16 v[0:3], v[184:187], v[216:219], v[0:3]
	v_mfma_f32_16x16x32_bf16 v[16:19], v[180:183], v[204:207], v[16:19]
	v_mfma_f32_16x16x32_bf16 v[16:19], v[184:187], v[208:211], v[16:19]
	s_setprio 2
	s_barrier
; #define PG8_STAGE(bufoff, gbase, voff) do { _Pragma("unroll") for (int _i = 0; _i < 2; ++_i) \
;         __builtin_amdgcn_global_load_lds((const unsigned*)((const char*)(gbase) + (voff)[_i]), (PG8_LAS unsigned*)(lds + (bufoff) + ldsw + _i * 8192), 16, 0, 0); } while (0)
; #define PG8_LDA(dst, b, h) do { _Pragma("unroll") for (int m = 0; m < 4; ++m) _Pragma("unroll") for (int k = 0; k < 2; ++k) dst[m][k] = *(const PG8_LAS bf16x8*)(lds + PG8_SA(b, h) + aoff + m * 2048 + k * 1024); } while (0)
; #define PG8_LDB(dst, b, h) do { _Pragma("unroll") for (int n = 0; n < 2; ++n) _Pragma("unroll") for (int k = 0; k < 2; ++k) dst[n][k] = *(const PG8_LAS bf16x8*)(lds + PG8_SB(b, h) + boff + n * 2048 + k * 1024); } while (0)
; #define PG8_MMA(ai, bj, At, Bt) do { __builtin_amdgcn_s_setprio(1); _Pragma("unroll") for (int m = 0; m < 4; ++m) _Pragma("unroll") for (int n = 0; n < 2; ++n) _Pragma("unroll") for (int k = 0; k < 2; ++k) \
;         acc[ai][bj][m][n] = __builtin_amdgcn_mfma_f32_16x16x32_bf16(Bt[n][k], At[m][k], acc[ai][bj][m][n], 0, 0, 0); __builtin_amdgcn_s_setprio(0); } while (0)
; #define PG8_WAIT_V(n) asm volatile("s_waitcnt vmcnt(" #n ")" ::: "memory")
; template <class Epi, class Sched, bool ALIGN_EPI = false, bool SP2 = false>
; __device__ __forceinline__ void gemm_phase(PG8_LAS unsigned char* lds, const Gemm g, const Sched& S, const Epi& E) {
;     ...
;             PG8_LDB(B0, 0, 0); PG8_LDB(B1, 0, 1); PG8_SCHED; PG8_LDA(At, 0, 0); PG8_STAGE(PG8_SA(1, 1), a1 + hstep, voffA);
;             PG8_WAIT_V(8); PG8_WAIT_L(0); PG8_BAR; PG8_MMA(0, 0, At, B0); PG8_MMA(0, 1, At, B1); PG8_BAR; PG8_SCHED;
;             PG8_LDA(At, 0, 1); PG8_STAGE(PG8_SB(0, 0), b2, voffB); PG8_STAGE(PG8_SB(0, 1), b2 + hstep, voffB); PG8_STAGE(PG8_SA(0, 0), a2, voffA);
;             PG8_WAIT_V(8); PG8_WAIT_L(0); PG8_BAR; PG8_MMA(1, 0, At, B0); PG8_MMA(1, 1, At, B1); PG8_BAR; PG8_SCHED;
;             PG8_LDB(B0, 1, 0); PG8_LDB(B1, 1, 1); PG8_SCHED; PG8_LDA(At, 1, 0); PG8_STAGE(PG8_SA(0, 1), a2 + hstep, voffA);
;             PG8_WAIT_V(8); PG8_WAIT_L(0); PG8_BAR; PG8_MMA(0, 0, At, B0); PG8_MMA(0, 1, At, B1); PG8_BAR; PG8_SCHED;
;             PG8_LDA(At, 1, 1); PG8_STAGE(PG8_SB(1, 0), b3, voffB); PG8_STAGE(PG8_SB(1, 1), b3 + hstep, voffB); PG8_STAGE(PG8_SA(1, 0), a3, voffA);
;             PG8_WAIT_V(8); PG8_WAIT_L(0); PG8_BAR; PG8_MMA(1, 0, At, B0); PG8_MMA(1, 1, At, B1); PG8_BAR; PG8_SCHED;
	v_mfma_f32_16x16x32_bf16 v[32:35], v[180:183], v[196:199], v[32:35]
	v_mfma_f32_16x16x32_bf16 v[32:35], v[184:187], v[200:203], v[32:35]
	v_mfma_f32_16x16x32_bf16 v[48:51], v[180:183], v[188:191], v[48:51]
	v_mfma_f32_16x16x32_bf16 v[48:51], v[184:187], v[192:195], v[48:51]
	s_setprio 0
	s_add_i32 s62, 0, 0x18000
	v_add_u32_e32 v159, s62, v153
	s_add_i32 s63, 0, 0x1c000
	ds_read_b128 v[144:147], v159
	ds_read_b128 v[160:163], v159 offset:1024
	ds_read_b128 v[164:167], v159 offset:2048
	ds_read_b128 v[168:171], v159 offset:3072
	v_add_u32_e32 v159, s63, v153
	ds_read_b128 v[172:175], v159
	ds_read_b128 v[176:179], v159 offset:1024
	ds_read_b128 v[180:183], v159 offset:2048
	ds_read_b128 v[184:187], v159 offset:3072
	s_add_u32 s80, s80, 0x160000
	s_addc_u32 s81, s81, 0
	s_mov_b32 m0, s61
	ds_read_b128 v[188:191], v157 offset:32768
	ds_read_b128 v[192:195], v157 offset:33792
	ds_read_b128 v[196:199], v157 offset:34816
	ds_read_b128 v[200:203], v157 offset:35840
	ds_read_b128 v[204:207], v157 offset:36864
	ds_read_b128 v[208:211], v157 offset:37888
	ds_read_b128 v[212:215], v157 offset:38912
	ds_read_b128 v[216:219], v157 offset:39936
	global_load_lds_dwordx4 v128, s[80:81]
	s_mov_b32 m0, s65
	s_nop 0
	global_load_lds_dwordx4 v132, s[80:81]
	s_waitcnt vmcnt(8)
	s_waitcnt lgkmcnt(0)
	s_setprio 1
	s_barrier
	v_mfma_f32_16x16x32_bf16 v[124:127], v[144:147], v[188:191], v[124:127]
	v_mfma_f32_16x16x32_bf16 v[124:127], v[160:163], v[192:195], v[124:127]
	v_mfma_f32_16x16x32_bf16 v[108:111], v[144:147], v[196:199], v[108:111]
	v_mfma_f32_16x16x32_bf16 v[108:111], v[160:163], v[200:203], v[108:111]
	v_mfma_f32_16x16x32_bf16 v[92:95], v[144:147], v[204:207], v[92:95]
	v_mfma_f32_16x16x32_bf16 v[92:95], v[160:163], v[208:211], v[92:95]
	v_mfma_f32_16x16x32_bf16 v[76:79], v[144:147], v[212:215], v[76:79]
	v_mfma_f32_16x16x32_bf16 v[76:79], v[160:163], v[216:219], v[76:79]
	v_mfma_f32_16x16x32_bf16 v[72:75], v[164:167], v[212:215], v[72:75]
	v_mfma_f32_16x16x32_bf16 v[72:75], v[168:171], v[216:219], v[72:75]
	v_mfma_f32_16x16x32_bf16 v[88:91], v[164:167], v[204:207], v[88:91]
	v_mfma_f32_16x16x32_bf16 v[88:91], v[168:171], v[208:211], v[88:91]
	v_mfma_f32_16x16x32_bf16 v[104:107], v[164:167], v[196:199], v[104:107]
	v_mfma_f32_16x16x32_bf16 v[104:107], v[168:171], v[200:203], v[104:107]
	v_mfma_f32_16x16x32_bf16 v[120:123], v[164:167], v[188:191], v[120:123]
	v_mfma_f32_16x16x32_bf16 v[120:123], v[168:171], v[192:195], v[120:123]
	v_mfma_f32_16x16x32_bf16 v[116:119], v[172:175], v[188:191], v[116:119]
	v_mfma_f32_16x16x32_bf16 v[116:119], v[176:179], v[192:195], v[116:119]
	v_mfma_f32_16x16x32_bf16 v[100:103], v[172:175], v[196:199], v[100:103]
	v_mfma_f32_16x16x32_bf16 v[100:103], v[176:179], v[200:203], v[100:103]
	v_mfma_f32_16x16x32_bf16 v[84:87], v[172:175], v[204:207], v[84:87]
	v_mfma_f32_16x16x32_bf16 v[84:87], v[176:179], v[208:211], v[84:87]
	v_mfma_f32_16x16x32_bf16 v[68:71], v[172:175], v[212:215], v[68:71]
	v_mfma_f32_16x16x32_bf16 v[68:71], v[176:179], v[216:219], v[68:71]
	v_mfma_f32_16x16x32_bf16 v[64:67], v[180:183], v[212:215], v[64:67]
	v_mfma_f32_16x16x32_bf16 v[64:67], v[184:187], v[216:219], v[64:67]
	v_mfma_f32_16x16x32_bf16 v[80:83], v[180:183], v[204:207], v[80:83]
	v_mfma_f32_16x16x32_bf16 v[80:83], v[184:187], v[208:211], v[80:83]
	s_setprio 2
	s_barrier
; #define PG8_STAGE(bufoff, gbase, voff) do { _Pragma("unroll") for (int _i = 0; _i < 2; ++_i) \
;         __builtin_amdgcn_global_load_lds((const unsigned*)((const char*)(gbase) + (voff)[_i]), (PG8_LAS unsigned*)(lds + (bufoff) + ldsw + _i * 8192), 16, 0, 0); } while (0)
; #define PG8_LDA(dst, b, h) do { _Pragma("unroll") for (int m = 0; m < 4; ++m) _Pragma("unroll") for (int k = 0; k < 2; ++k) dst[m][k] = *(const PG8_LAS bf16x8*)(lds + PG8_SA(b, h) + aoff + m * 2048 + k * 1024); } while (0)
; #define PG8_LDB(dst, b, h) do { _Pragma("unroll") for (int n = 0; n < 2; ++n) _Pragma("unroll") for (int k = 0; k < 2; ++k) dst[n][k] = *(const PG8_LAS bf16x8*)(lds + PG8_SB(b, h) + boff + n * 2048 + k * 1024); } while (0)
; #define PG8_MMA(ai, bj, At, Bt) do { __builtin_amdgcn_s_setprio(1); _Pragma("unroll") for (int m = 0; m < 4; ++m) _Pragma("unroll") for (int n = 0; n < 2; ++n) _Pragma("unroll") for (int k = 0; k < 2; ++k) \
;         acc[ai][bj][m][n] = __builtin_amdgcn_mfma_f32_16x16x32_bf16(Bt[n][k], At[m][k], acc[ai][bj][m][n], 0, 0, 0); __builtin_amdgcn_s_setprio(0); } while (0)
; #define PG8_WAIT_V(n) asm volatile("s_waitcnt vmcnt(" #n ")" ::: "memory")
; template <class Epi, class Sched, bool ALIGN_EPI = false, bool SP2 = false>
; __device__ __forceinline__ void gemm_phase(PG8_LAS unsigned char* lds, const Gemm g, const Sched& S, const Epi& E) {
;     ...
;             PG8_LDB(B0, 0, 0); PG8_LDB(B1, 0, 1); PG8_SCHED; PG8_LDA(At, 0, 0); PG8_STAGE(PG8_SA(1, 1), a1 + hstep, voffA);
;             PG8_WAIT_V(8); PG8_WAIT_L(0); PG8_BAR; PG8_MMA(0, 0, At, B0); PG8_MMA(0, 1, At, B1); PG8_BAR; PG8_SCHED;
;             PG8_LDA(At, 0, 1); PG8_STAGE(PG8_SB(0, 0), b2, voffB); PG8_STAGE(PG8_SB(0, 1), b2 + hstep, voffB); PG8_STAGE(PG8_SA(0, 0), a2, voffA);
;             PG8_WAIT_V(8); PG8_WAIT_L(0); PG8_BAR; PG8_MMA(1, 0, At, B0); PG8_MMA(1, 1, At, B1); PG8_BAR; PG8_SCHED;
;             PG8_LDB(B0, 1, 0); PG8_LDB(B1, 1, 1); PG8_SCHED; PG8_LDA(At, 1, 0); PG8_STAGE(PG8_SA(0, 1), a2 + hstep, voffA);
;             PG8_WAIT_V(8); PG8_WAIT_L(0); PG8_BAR; PG8_MMA(0, 0, At, B0); PG8_MMA(0, 1, At, B1); PG8_BAR; PG8_SCHED;
;             PG8_LDA(At, 1, 1); PG8_STAGE(PG8_SB(1, 0), b3, voffB); PG8_STAGE(PG8_SB(1, 1), b3 + hstep, voffB); PG8_STAGE(PG8_SA(1, 0), a3, voffA);
;             PG8_WAIT_V(8); PG8_WAIT_L(0); PG8_BAR; PG8_MMA(1, 0, At, B0); PG8_MMA(1, 1, At, B1); PG8_BAR; PG8_SCHED;
	v_mfma_f32_16x16x32_bf16 v[96:99], v[180:183], v[196:199], v[96:99]
	v_mfma_f32_16x16x32_bf16 v[96:99], v[184:187], v[200:203], v[96:99]
	v_mfma_f32_16x16x32_bf16 v[112:115], v[180:183], v[188:191], v[112:115]
	v_mfma_f32_16x16x32_bf16 v[112:115], v[184:187], v[192:195], v[112:115]
	s_setprio 0
	s_add_i32 s62, s62, s35
	v_lshl_add_u64 v[220:221], v[220:221], 0, s[56:57]
	s_mov_b32 m0, s62
	ds_read_b128 v[188:191], v157 offset:49152
	ds_read_b128 v[192:195], v157 offset:50176
	ds_read_b128 v[196:199], v157 offset:51200
	ds_read_b128 v[200:203], v157 offset:52224
	ds_read_b128 v[204:207], v157 offset:53248
	ds_read_b128 v[208:211], v157 offset:54272
	ds_read_b128 v[212:215], v157 offset:55296
	ds_read_b128 v[216:219], v157 offset:56320
	global_load_lds_dwordx4 v[220:221], off
	s_add_i32 m0, s62, 0x2000
	s_add_u32 s78, s78, 0x160080
	v_lshl_add_u64 v[220:221], v[222:223], 0, s[56:57]
	s_addc_u32 s79, s79, 0
	s_add_i32 s62, s63, s35
	global_load_lds_dwordx4 v[220:221], off
	s_mov_b32 m0, s62
	s_nop 0
	global_load_lds_dwordx4 v130, s[78:79]
	s_add_i32 m0, s62, 0x2000
	s_nop 0
	global_load_lds_dwordx4 v134, s[78:79]
	v_lshl_add_u64 v[220:221], v[224:225], 0, s[56:57]
	s_mov_b32 m0, s83
	s_nop 0
	global_load_lds_dwordx4 v[220:221], off
	v_lshl_add_u64 v[220:221], v[226:227], 0, s[56:57]
	s_mov_b32 m0, s84
	s_nop 0
	global_load_lds_dwordx4 v[220:221], off
	s_waitcnt vmcnt(8)
	s_waitcnt lgkmcnt(0)
	s_setprio 1
	s_barrier
	v_mfma_f32_16x16x32_bf16 v[60:63], v[144:147], v[188:191], v[60:63]
	v_mfma_f32_16x16x32_bf16 v[60:63], v[160:163], v[192:195], v[60:63]
	v_mfma_f32_16x16x32_bf16 v[44:47], v[144:147], v[196:199], v[44:47]
	v_mfma_f32_16x16x32_bf16 v[44:47], v[160:163], v[200:203], v[44:47]
	v_mfma_f32_16x16x32_bf16 v[28:31], v[144:147], v[204:207], v[28:31]
	v_mfma_f32_16x16x32_bf16 v[28:31], v[160:163], v[208:211], v[28:31]
	v_mfma_f32_16x16x32_bf16 v[12:15], v[144:147], v[212:215], v[12:15]
	v_mfma_f32_16x16x32_bf16 v[12:15], v[160:163], v[216:219], v[12:15]
	v_mfma_f32_16x16x32_bf16 v[8:11], v[164:167], v[212:215], v[8:11]
	v_mfma_f32_16x16x32_bf16 v[8:11], v[168:171], v[216:219], v[8:11]
	v_mfma_f32_16x16x32_bf16 v[24:27], v[164:167], v[204:207], v[24:27]
	v_mfma_f32_16x16x32_bf16 v[24:27], v[168:171], v[208:211], v[24:27]
	v_mfma_f32_16x16x32_bf16 v[40:43], v[164:167], v[196:199], v[40:43]
	v_mfma_f32_16x16x32_bf16 v[40:43], v[168:171], v[200:203], v[40:43]
	v_mfma_f32_16x16x32_bf16 v[56:59], v[164:167], v[188:191], v[56:59]
	v_mfma_f32_16x16x32_bf16 v[56:59], v[168:171], v[192:195], v[56:59]
	v_mfma_f32_16x16x32_bf16 v[52:55], v[172:175], v[188:191], v[52:55]
	v_mfma_f32_16x16x32_bf16 v[52:55], v[176:179], v[192:195], v[52:55]
	v_mfma_f32_16x16x32_bf16 v[36:39], v[172:175], v[196:199], v[36:39]
	v_mfma_f32_16x16x32_bf16 v[36:39], v[176:179], v[200:203], v[36:39]
	v_mfma_f32_16x16x32_bf16 v[20:23], v[172:175], v[204:207], v[20:23]
	v_mfma_f32_16x16x32_bf16 v[20:23], v[176:179], v[208:211], v[20:23]
	v_mfma_f32_16x16x32_bf16 v[4:7], v[172:175], v[212:215], v[4:7]
	v_mfma_f32_16x16x32_bf16 v[4:7], v[176:179], v[216:219], v[4:7]
	v_mfma_f32_16x16x32_bf16 v[0:3], v[180:183], v[212:215], v[0:3]
	v_mfma_f32_16x16x32_bf16 v[0:3], v[184:187], v[216:219], v[0:3]
	v_mfma_f32_16x16x32_bf16 v[16:19], v[180:183], v[204:207], v[16:19]
	v_mfma_f32_16x16x32_bf16 v[16:19], v[184:187], v[208:211], v[16:19]
	s_setprio 2
	s_barrier
	v_mfma_f32_16x16x32_bf16 v[32:35], v[180:183], v[196:199], v[32:35]
	v_mfma_f32_16x16x32_bf16 v[32:35], v[184:187], v[200:203], v[32:35]
	v_mfma_f32_16x16x32_bf16 v[48:51], v[180:183], v[188:191], v[48:51]
	v_mfma_f32_16x16x32_bf16 v[48:51], v[184:187], v[192:195], v[48:51]
	s_setprio 0
	s_add_i32 s92, s92, 2
	s_add_u32 s76, s76, 0x100
	s_addc_u32 s77, s77, 0
	s_add_u32 s50, s50, 0x100
	s_addc_u32 s91, s91, 0
	s_cmpk_gt_u32 s92, 0x55
	s_cbranch_scc0 .LBB0_179
	s_and_b64 vcc, exec, s[58:59]
	s_cbranch_vccz .LBB0_182
	s_barrier

; #define PG8_STAGE(bufoff, gbase, voff) do { _Pragma("unroll") for (int _i = 0; _i < 2; ++_i) \
;         __builtin_amdgcn_global_load_lds((const unsigned*)((const char*)(gbase) + (voff)[_i]), (PG8_LAS unsigned*)(lds + (bufoff) + ldsw + _i * 8192), 16, 0, 0); } while (0)
; #define PG8_LDA(dst, b, h) do { _Pragma("unroll") for (int m = 0; m < 4; ++m) _Pragma("unroll") for (int k = 0; k < 2; ++k) dst[m][k] = *(const PG8_LAS bf16x8*)(lds + PG8_SA(b, h) + aoff + m * 2048 + k * 1024); } while (0)
; #define PG8_LDB(dst, b, h) do { _Pragma("unroll") for (int n = 0; n < 2; ++n) _Pragma("unroll") for (int k = 0; k < 2; ++k) dst[n][k] = *(const PG8_LAS bf16x8*)(lds + PG8_SB(b, h) + boff + n * 2048 + k * 1024); } while (0)
; template <class Epi, class Sched, bool ALIGN_EPI = false, bool SP2 = false>
; __device__ __forceinline__ void gemm_phase(PG8_LAS unsigned char* lds, const Gemm g, const Sched& S, const Epi& E) {
;     ...
;         for (int t = 0; t < nt; t += 2) {
;             const bool last = (t == nt - 2);
;             const char* a1 = cA + (size_t)(t + 1) * kstep;
;             const char* a2 = last ? nA : cA + (size_t)(t + 2) * kstep; const char* b2 = last ? nB : cB + (size_t)(t + 2) * kstep;
;             const char* a3 = a2 + kstep; const char* b3 = b2 + kstep;
;             if (last && has_next) S.a_ready(nxt);
;             if constexpr (SP2) {
;             PG8_LDB(B0, 0, 0); PG8_LDB(B1, 0, 1); PG8_SCHED; PG8_LDA(At, 0, 0); PG8_STAGE(PG8_SA(1, 1), a1 + hstep, voffA);
;             PG8_WAIT_V(8); PG8_WAIT_L(0); PG8_BAR; PG8_MMA(0, 0, At, B0); PG8_MMA(0, 1, At, B1); PG8_BAR; PG8_SCHED;
;             PG8_LDA(At, 0, 1); PG8_STAGE(PG8_SB(0, 0), b2, voffB); PG8_STAGE(PG8_SB(0, 1), b2 + hstep, voffB); PG8_STAGE(PG8_SA(0, 0), a2, voffA);
;             PG8_WAIT_V(8); PG8_WAIT_L(0); PG8_BAR; PG8_MMA(1, 0, At, B0); PG8_MMA(1, 1, At, B1); PG8_BAR; PG8_SCHED;
;             PG8_LDB(B0, 1, 0); PG8_LDB(B1, 1, 1); PG8_SCHED; PG8_LDA(At, 1, 0); PG8_STAGE(PG8_SA(0, 1), a2 + hstep, voffA);
;             PG8_WAIT_V(8); PG8_WAIT_L(0); PG8_BAR; PG8_MMA(0, 0, At, B0); PG8_MMA(0, 1, At, B1); PG8_BAR; PG8_SCHED;
;             PG8_LDA(At, 1, 1); PG8_STAGE(PG8_SB(1, 0), b3, voffB); PG8_STAGE(PG8_SB(1, 1), b3 + hstep, voffB); PG8_STAGE(PG8_SA(1, 0), a3, voffA);
;             PG8_WAIT_V(8); PG8_WAIT_L(0); PG8_BAR; PG8_MMA(1, 0, At, B0); PG8_MMA(1, 1, At, B1); PG8_BAR; PG8_SCHED;
.LBB0_326:
	ds_read_b128 v[178:181], v176
	ds_read_b128 v[182:185], v176 offset:1024
	ds_read_b128 v[186:189], v176 offset:2048
	ds_read_b128 v[190:193], v176 offset:3072
	ds_read_b128 v[194:197], v177
	ds_read_b128 v[198:201], v177 offset:1024
	ds_read_b128 v[202:205], v177 offset:2048
	ds_read_b128 v[206:209], v177 offset:3072
	s_add_u32 s62, s76, 0xfff80080
	s_addc_u32 s63, s77, -1
	s_cmp_eq_u32 s75, 28
	s_cselect_b32 s81, s10, s63
	s_cselect_b32 s80, s11, s62
	s_cselect_b32 s79, s51, s67
	s_cselect_b32 s78, s55, s57
	s_add_i32 m0, s64, 0xc000
	ds_read_b128 v[210:213], v145
	ds_read_b128 v[214:217], v145 offset:1024
	ds_read_b128 v[218:221], v145 offset:2048
	ds_read_b128 v[222:225], v145 offset:3072
	ds_read_b128 v[226:229], v145 offset:4096
	ds_read_b128 v[230:233], v145 offset:5120
	ds_read_b128 v[234:237], v145 offset:6144
	ds_read_b128 v[238:241], v145 offset:7168
	global_load_lds_dwordx4 v146, s[76:77]
	s_add_i32 m0, s64, 0xe000
	s_nop 0
	global_load_lds_dwordx4 v152, s[76:77]
	s_waitcnt vmcnt(8)
	s_waitcnt lgkmcnt(0)
	s_setprio 1
	s_barrier
	v_mfma_f32_16x16x32_bf16 v[124:127], v[178:181], v[210:213], v[124:127]
	v_mfma_f32_16x16x32_bf16 v[124:127], v[182:185], v[214:217], v[124:127]
	v_mfma_f32_16x16x32_bf16 v[116:119], v[178:181], v[218:221], v[116:119]
	v_mfma_f32_16x16x32_bf16 v[116:119], v[182:185], v[222:225], v[116:119]
	v_mfma_f32_16x16x32_bf16 v[108:111], v[178:181], v[226:229], v[108:111]
	v_mfma_f32_16x16x32_bf16 v[108:111], v[182:185], v[230:233], v[108:111]
	v_mfma_f32_16x16x32_bf16 v[100:103], v[178:181], v[234:237], v[100:103]
	v_mfma_f32_16x16x32_bf16 v[100:103], v[182:185], v[238:241], v[100:103]
	v_mfma_f32_16x16x32_bf16 v[96:99], v[186:189], v[234:237], v[96:99]
	v_mfma_f32_16x16x32_bf16 v[96:99], v[190:193], v[238:241], v[96:99]
	v_mfma_f32_16x16x32_bf16 v[104:107], v[186:189], v[226:229], v[104:107]
	v_mfma_f32_16x16x32_bf16 v[104:107], v[190:193], v[230:233], v[104:107]
	v_mfma_f32_16x16x32_bf16 v[112:115], v[186:189], v[218:221], v[112:115]
	v_mfma_f32_16x16x32_bf16 v[112:115], v[190:193], v[222:225], v[112:115]
	v_mfma_f32_16x16x32_bf16 v[120:123], v[186:189], v[210:213], v[120:123]
	v_mfma_f32_16x16x32_bf16 v[120:123], v[190:193], v[214:217], v[120:123]
	v_mfma_f32_16x16x32_bf16 v[68:71], v[194:197], v[210:213], v[68:71]
	v_mfma_f32_16x16x32_bf16 v[68:71], v[198:201], v[214:217], v[68:71]
	v_mfma_f32_16x16x32_bf16 v[52:55], v[194:197], v[218:221], v[52:55]
	v_mfma_f32_16x16x32_bf16 v[52:55], v[198:201], v[222:225], v[52:55]
	v_mfma_f32_16x16x32_bf16 v[44:47], v[194:197], v[226:229], v[44:47]
	v_mfma_f32_16x16x32_bf16 v[44:47], v[198:201], v[230:233], v[44:47]
	v_mfma_f32_16x16x32_bf16 v[36:39], v[194:197], v[234:237], v[36:39]
	v_mfma_f32_16x16x32_bf16 v[36:39], v[198:201], v[238:241], v[36:39]
	v_mfma_f32_16x16x32_bf16 v[32:35], v[202:205], v[234:237], v[32:35]
	v_mfma_f32_16x16x32_bf16 v[32:35], v[206:209], v[238:241], v[32:35]
	v_mfma_f32_16x16x32_bf16 v[40:43], v[202:205], v[226:229], v[40:43]
	v_mfma_f32_16x16x32_bf16 v[40:43], v[206:209], v[230:233], v[40:43]
	s_setprio 2
	s_barrier
	v_mfma_f32_16x16x32_bf16 v[48:51], v[202:205], v[218:221], v[48:51]
	v_mfma_f32_16x16x32_bf16 v[48:51], v[206:209], v[222:225], v[48:51]
	v_mfma_f32_16x16x32_bf16 v[64:67], v[202:205], v[210:213], v[64:67]
	v_mfma_f32_16x16x32_bf16 v[64:67], v[206:209], v[214:217], v[64:67]
	s_setprio 0
	s_add_i32 s62, s53, s3
	v_lshl_add_u64 v[166:167], s[78:79], 0, v[130:131]
	s_mov_b32 m0, s62
	ds_read_b128 v[210:213], v145 offset:16384
	ds_read_b128 v[214:217], v145 offset:17408
	ds_read_b128 v[218:221], v145 offset:18432
	ds_read_b128 v[222:225], v145 offset:19456
	ds_read_b128 v[226:229], v145 offset:20480
	ds_read_b128 v[230:233], v145 offset:21504
	ds_read_b128 v[234:237], v145 offset:22528
	ds_read_b128 v[238:241], v145 offset:23552
	global_load_lds_dwordx4 v130, s[78:79]
	s_add_i32 m0, s62, 0x2000
	s_add_u32 s82, s78, 0x80000
	v_lshl_add_u64 v[242:243], s[78:79], 0, v[134:135]
	s_addc_u32 s83, s79, 0
	s_add_i32 s62, s66, s3
	global_load_lds_dwordx4 v134, s[78:79]
	s_mov_b32 m0, s62
	v_lshl_add_u64 v[246:247], s[80:81], 0, v[132:133]
	global_load_lds_dwordx4 v130, s[82:83]
	s_add_i32 m0, s62, 0x2000
	s_nop 0
	global_load_lds_dwordx4 v134, s[82:83]
	v_lshl_add_u64 v[244:245], s[80:81], 0, v[128:129]
	s_mov_b32 m0, s64
	s_nop 0
	global_load_lds_dwordx4 v128, s[80:81]
	s_mov_b32 m0, s65
	s_nop 0
	global_load_lds_dwordx4 v132, s[80:81]
	s_waitcnt vmcnt(8)
	s_waitcnt lgkmcnt(0)
	s_setprio 1
	s_barrier
	v_mfma_f32_16x16x32_bf16 v[92:95], v[178:181], v[210:213], v[92:95]
	v_mfma_f32_16x16x32_bf16 v[92:95], v[182:185], v[214:217], v[92:95]
	v_mfma_f32_16x16x32_bf16 v[84:87], v[178:181], v[218:221], v[84:87]
	v_mfma_f32_16x16x32_bf16 v[84:87], v[182:185], v[222:225], v[84:87]
	v_mfma_f32_16x16x32_bf16 v[76:79], v[178:181], v[226:229], v[76:79]
	v_mfma_f32_16x16x32_bf16 v[76:79], v[182:185], v[230:233], v[76:79]
	v_mfma_f32_16x16x32_bf16 v[60:63], v[178:181], v[234:237], v[60:63]
	v_mfma_f32_16x16x32_bf16 v[60:63], v[182:185], v[238:241], v[60:63]
	v_mfma_f32_16x16x32_bf16 v[56:59], v[186:189], v[234:237], v[56:59]
	v_mfma_f32_16x16x32_bf16 v[56:59], v[190:193], v[238:241], v[56:59]
	v_mfma_f32_16x16x32_bf16 v[72:75], v[186:189], v[226:229], v[72:75]
	v_mfma_f32_16x16x32_bf16 v[72:75], v[190:193], v[230:233], v[72:75]
	v_mfma_f32_16x16x32_bf16 v[80:83], v[186:189], v[218:221], v[80:83]
	v_mfma_f32_16x16x32_bf16 v[80:83], v[190:193], v[222:225], v[80:83]
	v_mfma_f32_16x16x32_bf16 v[88:91], v[186:189], v[210:213], v[88:91]
	v_mfma_f32_16x16x32_bf16 v[88:91], v[190:193], v[214:217], v[88:91]
	v_mfma_f32_16x16x32_bf16 v[28:31], v[194:197], v[210:213], v[28:31]
	v_mfma_f32_16x16x32_bf16 v[28:31], v[198:201], v[214:217], v[28:31]
	v_mfma_f32_16x16x32_bf16 v[20:23], v[194:197], v[218:221], v[20:23]
	v_mfma_f32_16x16x32_bf16 v[20:23], v[198:201], v[222:225], v[20:23]
	v_mfma_f32_16x16x32_bf16 v[12:15], v[194:197], v[226:229], v[12:15]
	v_mfma_f32_16x16x32_bf16 v[12:15], v[198:201], v[230:233], v[12:15]
	v_mfma_f32_16x16x32_bf16 v[4:7], v[194:197], v[234:237], v[4:7]
	v_mfma_f32_16x16x32_bf16 v[4:7], v[198:201], v[238:241], v[4:7]
	v_mfma_f32_16x16x32_bf16 v[0:3], v[202:205], v[234:237], v[0:3]
	v_mfma_f32_16x16x32_bf16 v[0:3], v[206:209], v[238:241], v[0:3]
	v_mfma_f32_16x16x32_bf16 v[8:11], v[202:205], v[226:229], v[8:11]
	v_mfma_f32_16x16x32_bf16 v[8:11], v[206:209], v[230:233], v[8:11]
	s_setprio 2
	s_barrier
; #define PG8_STAGE(bufoff, gbase, voff) do { _Pragma("unroll") for (int _i = 0; _i < 2; ++_i) \
;         __builtin_amdgcn_global_load_lds((const unsigned*)((const char*)(gbase) + (voff)[_i]), (PG8_LAS unsigned*)(lds + (bufoff) + ldsw + _i * 8192), 16, 0, 0); } while (0)
; #define PG8_LDA(dst, b, h) do { _Pragma("unroll") for (int m = 0; m < 4; ++m) _Pragma("unroll") for (int k = 0; k < 2; ++k) dst[m][k] = *(const PG8_LAS bf16x8*)(lds + PG8_SA(b, h) + aoff + m * 2048 + k * 1024); } while (0)
; #define PG8_LDB(dst, b, h) do { _Pragma("unroll") for (int n = 0; n < 2; ++n) _Pragma("unroll") for (int k = 0; k < 2; ++k) dst[n][k] = *(const PG8_LAS bf16x8*)(lds + PG8_SB(b, h) + boff + n * 2048 + k * 1024); } while (0)
; #define PG8_MMA(ai, bj, At, Bt) do { __builtin_amdgcn_s_setprio(1); _Pragma("unroll") for (int m = 0; m < 4; ++m) _Pragma("unroll") for (int n = 0; n < 2; ++n) _Pragma("unroll") for (int k = 0; k < 2; ++k) \
;         acc[ai][bj][m][n] = __builtin_amdgcn_mfma_f32_16x16x32_bf16(Bt[n][k], At[m][k], acc[ai][bj][m][n], 0, 0, 0); __builtin_amdgcn_s_setprio(0); } while (0)
; #define PG8_WAIT_V(n) asm volatile("s_waitcnt vmcnt(" #n ")" ::: "memory")
; template <class Epi, class Sched, bool ALIGN_EPI = false, bool SP2 = false>
; __device__ __forceinline__ void gemm_phase(PG8_LAS unsigned char* lds, const Gemm g, const Sched& S, const Epi& E) {
;     ...
;             PG8_LDB(B0, 0, 0); PG8_LDB(B1, 0, 1); PG8_SCHED; PG8_LDA(At, 0, 0); PG8_STAGE(PG8_SA(1, 1), a1 + hstep, voffA);
;             PG8_WAIT_V(8); PG8_WAIT_L(0); PG8_BAR; PG8_MMA(0, 0, At, B0); PG8_MMA(0, 1, At, B1); PG8_BAR; PG8_SCHED;
;             PG8_LDA(At, 0, 1); PG8_STAGE(PG8_SB(0, 0), b2, voffB); PG8_STAGE(PG8_SB(0, 1), b2 + hstep, voffB); PG8_STAGE(PG8_SA(0, 0), a2, voffA);
;             PG8_WAIT_V(8); PG8_WAIT_L(0); PG8_BAR; PG8_MMA(1, 0, At, B0); PG8_MMA(1, 1, At, B1); PG8_BAR; PG8_SCHED;
;             PG8_LDB(B0, 1, 0); PG8_LDB(B1, 1, 1); PG8_SCHED; PG8_LDA(At, 1, 0); PG8_STAGE(PG8_SA(0, 1), a2 + hstep, voffA);
;             PG8_WAIT_V(8); PG8_WAIT_L(0); PG8_BAR; PG8_MMA(0, 0, At, B0); PG8_MMA(0, 1, At, B1); PG8_BAR; PG8_SCHED;
;             PG8_LDA(At, 1, 1); PG8_STAGE(PG8_SB(1, 0), b3, voffB); PG8_STAGE(PG8_SB(1, 1), b3 + hstep, voffB); PG8_STAGE(PG8_SA(1, 0), a3, voffA);
;             PG8_WAIT_V(8); PG8_WAIT_L(0); PG8_BAR; PG8_MMA(1, 0, At, B0); PG8_MMA(1, 1, At, B1); PG8_BAR; PG8_SCHED;
	v_mfma_f32_16x16x32_bf16 v[16:19], v[202:205], v[218:221], v[16:19]
	v_mfma_f32_16x16x32_bf16 v[16:19], v[206:209], v[222:225], v[16:19]
	v_mfma_f32_16x16x32_bf16 v[24:27], v[202:205], v[210:213], v[24:27]
	v_mfma_f32_16x16x32_bf16 v[24:27], v[206:209], v[214:217], v[24:27]
	s_setprio 0
	s_add_i32 s62, 0, 0x18000
	s_add_i32 s63, 0, 0x1c000
	v_add_u32_e32 v190, s62, v143
	v_add_u32_e32 v206, s63, v143
	ds_read_b128 v[178:181], v190
	ds_read_b128 v[182:185], v190 offset:1024
	ds_read_b128 v[186:189], v190 offset:2048
	ds_read_b128 v[190:193], v190 offset:3072
	ds_read_b128 v[194:197], v206
	ds_read_b128 v[198:201], v206 offset:1024
	ds_read_b128 v[202:205], v206 offset:2048
	ds_read_b128 v[206:209], v206 offset:3072
	s_add_u32 s80, s80, 0x80000
	s_addc_u32 s81, s81, 0
	s_mov_b32 m0, s86
	ds_read_b128 v[210:213], v145 offset:32768
	ds_read_b128 v[214:217], v145 offset:33792
	ds_read_b128 v[218:221], v145 offset:34816
	ds_read_b128 v[222:225], v145 offset:35840
	ds_read_b128 v[226:229], v145 offset:36864
	ds_read_b128 v[230:233], v145 offset:37888
	ds_read_b128 v[234:237], v145 offset:38912
	ds_read_b128 v[238:241], v145 offset:39936
	global_load_lds_dwordx4 v128, s[80:81]
	s_mov_b32 m0, s87
	s_nop 0
	global_load_lds_dwordx4 v132, s[80:81]
	s_waitcnt vmcnt(8)
	s_waitcnt lgkmcnt(0)
	s_setprio 1
	s_barrier
	v_mfma_f32_16x16x32_bf16 v[124:127], v[178:181], v[210:213], v[124:127]
	v_mfma_f32_16x16x32_bf16 v[124:127], v[182:185], v[214:217], v[124:127]
	v_mfma_f32_16x16x32_bf16 v[116:119], v[178:181], v[218:221], v[116:119]
	v_mfma_f32_16x16x32_bf16 v[116:119], v[182:185], v[222:225], v[116:119]
	v_mfma_f32_16x16x32_bf16 v[108:111], v[178:181], v[226:229], v[108:111]
	v_mfma_f32_16x16x32_bf16 v[108:111], v[182:185], v[230:233], v[108:111]
	v_mfma_f32_16x16x32_bf16 v[100:103], v[178:181], v[234:237], v[100:103]
	v_mfma_f32_16x16x32_bf16 v[100:103], v[182:185], v[238:241], v[100:103]
	v_mfma_f32_16x16x32_bf16 v[96:99], v[186:189], v[234:237], v[96:99]
	v_mfma_f32_16x16x32_bf16 v[96:99], v[190:193], v[238:241], v[96:99]
	v_mfma_f32_16x16x32_bf16 v[104:107], v[186:189], v[226:229], v[104:107]
	v_mfma_f32_16x16x32_bf16 v[104:107], v[190:193], v[230:233], v[104:107]
	v_mfma_f32_16x16x32_bf16 v[112:115], v[186:189], v[218:221], v[112:115]
	v_mfma_f32_16x16x32_bf16 v[112:115], v[190:193], v[222:225], v[112:115]
	v_mfma_f32_16x16x32_bf16 v[120:123], v[186:189], v[210:213], v[120:123]
	v_mfma_f32_16x16x32_bf16 v[120:123], v[190:193], v[214:217], v[120:123]
	v_mfma_f32_16x16x32_bf16 v[68:71], v[194:197], v[210:213], v[68:71]
	v_mfma_f32_16x16x32_bf16 v[68:71], v[198:201], v[214:217], v[68:71]
	v_mfma_f32_16x16x32_bf16 v[52:55], v[194:197], v[218:221], v[52:55]
	v_mfma_f32_16x16x32_bf16 v[52:55], v[198:201], v[222:225], v[52:55]
	v_mfma_f32_16x16x32_bf16 v[44:47], v[194:197], v[226:229], v[44:47]
	v_mfma_f32_16x16x32_bf16 v[44:47], v[198:201], v[230:233], v[44:47]
	v_mfma_f32_16x16x32_bf16 v[36:39], v[194:197], v[234:237], v[36:39]
	v_mfma_f32_16x16x32_bf16 v[36:39], v[198:201], v[238:241], v[36:39]
	v_mfma_f32_16x16x32_bf16 v[32:35], v[202:205], v[234:237], v[32:35]
	v_mfma_f32_16x16x32_bf16 v[32:35], v[206:209], v[238:241], v[32:35]
	v_mfma_f32_16x16x32_bf16 v[40:43], v[202:205], v[226:229], v[40:43]
	v_mfma_f32_16x16x32_bf16 v[40:43], v[206:209], v[230:233], v[40:43]
	s_setprio 2
	s_barrier
; #define PG8_STAGE(bufoff, gbase, voff) do { _Pragma("unroll") for (int _i = 0; _i < 2; ++_i) \
;         __builtin_amdgcn_global_load_lds((const unsigned*)((const char*)(gbase) + (voff)[_i]), (PG8_LAS unsigned*)(lds + (bufoff) + ldsw + _i * 8192), 16, 0, 0); } while (0)
; #define PG8_LDA(dst, b, h) do { _Pragma("unroll") for (int m = 0; m < 4; ++m) _Pragma("unroll") for (int k = 0; k < 2; ++k) dst[m][k] = *(const PG8_LAS bf16x8*)(lds + PG8_SA(b, h) + aoff + m * 2048 + k * 1024); } while (0)
; #define PG8_LDB(dst, b, h) do { _Pragma("unroll") for (int n = 0; n < 2; ++n) _Pragma("unroll") for (int k = 0; k < 2; ++k) dst[n][k] = *(const PG8_LAS bf16x8*)(lds + PG8_SB(b, h) + boff + n * 2048 + k * 1024); } while (0)
; #define PG8_MMA(ai, bj, At, Bt) do { __builtin_amdgcn_s_setprio(1); _Pragma("unroll") for (int m = 0; m < 4; ++m) _Pragma("unroll") for (int n = 0; n < 2; ++n) _Pragma("unroll") for (int k = 0; k < 2; ++k) \
;         acc[ai][bj][m][n] = __builtin_amdgcn_mfma_f32_16x16x32_bf16(Bt[n][k], At[m][k], acc[ai][bj][m][n], 0, 0, 0); __builtin_amdgcn_s_setprio(0); } while (0)
; #define PG8_WAIT_V(n) asm volatile("s_waitcnt vmcnt(" #n ")" ::: "memory")
; template <class Epi, class Sched, bool ALIGN_EPI = false, bool SP2 = false>
; __device__ __forceinline__ void gemm_phase(PG8_LAS unsigned char* lds, const Gemm g, const Sched& S, const Epi& E) {
;     ...
;             PG8_LDB(B0, 0, 0); PG8_LDB(B1, 0, 1); PG8_SCHED; PG8_LDA(At, 0, 0); PG8_STAGE(PG8_SA(1, 1), a1 + hstep, voffA);
;             PG8_WAIT_V(8); PG8_WAIT_L(0); PG8_BAR; PG8_MMA(0, 0, At, B0); PG8_MMA(0, 1, At, B1); PG8_BAR; PG8_SCHED;
;             PG8_LDA(At, 0, 1); PG8_STAGE(PG8_SB(0, 0), b2, voffB); PG8_STAGE(PG8_SB(0, 1), b2 + hstep, voffB); PG8_STAGE(PG8_SA(0, 0), a2, voffA);
;             PG8_WAIT_V(8); PG8_WAIT_L(0); PG8_BAR; PG8_MMA(1, 0, At, B0); PG8_MMA(1, 1, At, B1); PG8_BAR; PG8_SCHED;
;             PG8_LDB(B0, 1, 0); PG8_LDB(B1, 1, 1); PG8_SCHED; PG8_LDA(At, 1, 0); PG8_STAGE(PG8_SA(0, 1), a2 + hstep, voffA);
;             PG8_WAIT_V(8); PG8_WAIT_L(0); PG8_BAR; PG8_MMA(0, 0, At, B0); PG8_MMA(0, 1, At, B1); PG8_BAR; PG8_SCHED;
;             PG8_LDA(At, 1, 1); PG8_STAGE(PG8_SB(1, 0), b3, voffB); PG8_STAGE(PG8_SB(1, 1), b3 + hstep, voffB); PG8_STAGE(PG8_SA(1, 0), a3, voffA);
;             PG8_WAIT_V(8); PG8_WAIT_L(0); PG8_BAR; PG8_MMA(1, 0, At, B0); PG8_MMA(1, 1, At, B1); PG8_BAR; PG8_SCHED;
	v_mfma_f32_16x16x32_bf16 v[48:51], v[202:205], v[218:221], v[48:51]
	v_mfma_f32_16x16x32_bf16 v[48:51], v[206:209], v[222:225], v[48:51]
	v_mfma_f32_16x16x32_bf16 v[64:67], v[202:205], v[210:213], v[64:67]
	v_mfma_f32_16x16x32_bf16 v[64:67], v[206:209], v[214:217], v[64:67]
	s_setprio 0
	s_add_i32 s62, s62, s3
	v_lshl_add_u64 v[166:167], v[166:167], 0, s[8:9]
	s_mov_b32 m0, s62
	ds_read_b128 v[210:213], v145 offset:49152
	ds_read_b128 v[214:217], v145 offset:50176
	ds_read_b128 v[218:221], v145 offset:51200
	ds_read_b128 v[222:225], v145 offset:52224
	ds_read_b128 v[226:229], v145 offset:53248
	ds_read_b128 v[230:233], v145 offset:54272
	ds_read_b128 v[234:237], v145 offset:55296
	ds_read_b128 v[238:241], v145 offset:56320
	global_load_lds_dwordx4 v[166:167], off
	s_add_i32 m0, s62, 0x2000
	s_add_u32 s78, s78, 0x80080
	v_lshl_add_u64 v[166:167], v[242:243], 0, s[8:9]
	s_addc_u32 s79, s79, 0
	s_add_i32 s62, s63, s3
	global_load_lds_dwordx4 v[166:167], off
	s_mov_b32 m0, s62
	s_nop 0
	global_load_lds_dwordx4 v130, s[78:79]
	s_add_i32 m0, s62, 0x2000
	s_nop 0
	global_load_lds_dwordx4 v134, s[78:79]
	v_lshl_add_u64 v[166:167], v[244:245], 0, s[8:9]
	s_mov_b32 m0, s89
	s_nop 0
	global_load_lds_dwordx4 v[166:167], off
	v_lshl_add_u64 v[166:167], v[246:247], 0, s[8:9]
	s_mov_b32 m0, s90
	s_nop 0
	global_load_lds_dwordx4 v[166:167], off
	s_waitcnt vmcnt(8)
	s_waitcnt lgkmcnt(0)
	s_setprio 1
	s_barrier
	v_mfma_f32_16x16x32_bf16 v[92:95], v[178:181], v[210:213], v[92:95]
	v_mfma_f32_16x16x32_bf16 v[92:95], v[182:185], v[214:217], v[92:95]
	v_mfma_f32_16x16x32_bf16 v[84:87], v[178:181], v[218:221], v[84:87]
	v_mfma_f32_16x16x32_bf16 v[84:87], v[182:185], v[222:225], v[84:87]
	v_mfma_f32_16x16x32_bf16 v[76:79], v[178:181], v[226:229], v[76:79]
	v_mfma_f32_16x16x32_bf16 v[76:79], v[182:185], v[230:233], v[76:79]
	v_mfma_f32_16x16x32_bf16 v[60:63], v[178:181], v[234:237], v[60:63]
	v_mfma_f32_16x16x32_bf16 v[60:63], v[182:185], v[238:241], v[60:63]
	v_mfma_f32_16x16x32_bf16 v[56:59], v[186:189], v[234:237], v[56:59]
	v_mfma_f32_16x16x32_bf16 v[56:59], v[190:193], v[238:241], v[56:59]
	v_mfma_f32_16x16x32_bf16 v[72:75], v[186:189], v[226:229], v[72:75]
	v_mfma_f32_16x16x32_bf16 v[72:75], v[190:193], v[230:233], v[72:75]
	v_mfma_f32_16x16x32_bf16 v[80:83], v[186:189], v[218:221], v[80:83]
	v_mfma_f32_16x16x32_bf16 v[80:83], v[190:193], v[222:225], v[80:83]
	v_mfma_f32_16x16x32_bf16 v[88:91], v[186:189], v[210:213], v[88:91]
	v_mfma_f32_16x16x32_bf16 v[88:91], v[190:193], v[214:217], v[88:91]
	v_mfma_f32_16x16x32_bf16 v[28:31], v[194:197], v[210:213], v[28:31]
	v_mfma_f32_16x16x32_bf16 v[28:31], v[198:201], v[214:217], v[28:31]
	v_mfma_f32_16x16x32_bf16 v[20:23], v[194:197], v[218:221], v[20:23]
	v_mfma_f32_16x16x32_bf16 v[20:23], v[198:201], v[222:225], v[20:23]
	v_mfma_f32_16x16x32_bf16 v[12:15], v[194:197], v[226:229], v[12:15]
	v_mfma_f32_16x16x32_bf16 v[12:15], v[198:201], v[230:233], v[12:15]
	v_mfma_f32_16x16x32_bf16 v[4:7], v[194:197], v[234:237], v[4:7]
	v_mfma_f32_16x16x32_bf16 v[4:7], v[198:201], v[238:241], v[4:7]
	v_mfma_f32_16x16x32_bf16 v[0:3], v[202:205], v[234:237], v[0:3]
	v_mfma_f32_16x16x32_bf16 v[0:3], v[206:209], v[238:241], v[0:3]
	v_mfma_f32_16x16x32_bf16 v[8:11], v[202:205], v[226:229], v[8:11]
	v_mfma_f32_16x16x32_bf16 v[8:11], v[206:209], v[230:233], v[8:11]
	s_setprio 2
	s_barrier
	v_mfma_f32_16x16x32_bf16 v[16:19], v[202:205], v[218:221], v[16:19]
	v_mfma_f32_16x16x32_bf16 v[16:19], v[206:209], v[222:225], v[16:19]
	v_mfma_f32_16x16x32_bf16 v[24:27], v[202:205], v[210:213], v[24:27]
	v_mfma_f32_16x16x32_bf16 v[24:27], v[206:209], v[214:217], v[24:27]
	s_setprio 0
	s_add_i32 s75, s75, 2
	s_add_u32 s76, s76, 0x100
	s_addc_u32 s77, s77, 0
	s_add_u32 s57, s57, 0x100
	s_addc_u32 s67, s67, 0
	s_cmp_gt_u32 s75, 29
	s_cbranch_scc0 .LBB0_326
	s_and_b64 vcc, exec, s[20:21]
	s_cbranch_vccz .LBB0_329
	s_barrier

; #define PG8_STAGE(bufoff, gbase, voff) do { _Pragma("unroll") for (int _i = 0; _i < 2; ++_i) \
;         __builtin_amdgcn_global_load_lds((const unsigned*)((const char*)(gbase) + (voff)[_i]), (PG8_LAS unsigned*)(lds + (bufoff) + ldsw + _i * 8192), 16, 0, 0); } while (0)
; #define PG8_LDA(dst, b, h) do { _Pragma("unroll") for (int m = 0; m < 4; ++m) _Pragma("unroll") for (int k = 0; k < 2; ++k) dst[m][k] = *(const PG8_LAS bf16x8*)(lds + PG8_SA(b, h) + aoff + m * 2048 + k * 1024); } while (0)
; #define PG8_LDB(dst, b, h) do { _Pragma("unroll") for (int n = 0; n < 2; ++n) _Pragma("unroll") for (int k = 0; k < 2; ++k) dst[n][k] = *(const PG8_LAS bf16x8*)(lds + PG8_SB(b, h) + boff + n * 2048 + k * 1024); } while (0)
; #define PG8_MMA(ai, bj, At, Bt) do { __builtin_amdgcn_s_setprio(1); _Pragma("unroll") for (int m = 0; m < 4; ++m) _Pragma("unroll") for (int n = 0; n < 2; ++n) _Pragma("unroll") for (int k = 0; k < 2; ++k) \
;         acc[ai][bj][m][n] = __builtin_amdgcn_mfma_f32_16x16x32_bf16(Bt[n][k], At[m][k], acc[ai][bj][m][n], 0, 0, 0); __builtin_amdgcn_s_setprio(0); } while (0)
; #define PG8_WAIT_V(n) asm volatile("s_waitcnt vmcnt(" #n ")" ::: "memory")
; #define PG8_WAIT_L(n) asm volatile("s_waitcnt lgkmcnt(" #n ")" ::: "memory")
; template <class Epi, class Sched, bool ALIGN_EPI = false, bool SP2 = false>
; __device__ __forceinline__ void gemm_phase(PG8_LAS unsigned char* lds, const Gemm g, const Sched& S, const Epi& E) {
;     ...
;             const bool last = (t == nt - 2);
;             const char* a1 = cA + (size_t)(t + 1) * kstep;
;             const char* a2 = last ? nA : cA + (size_t)(t + 2) * kstep; const char* b2 = last ? nB : cB + (size_t)(t + 2) * kstep;
;             const char* a3 = a2 + kstep; const char* b3 = b2 + kstep;
;             if (last && has_next) S.a_ready(nxt);
;             if constexpr (SP2) {
;             PG8_LDB(B0, 0, 0); PG8_LDB(B1, 0, 1); PG8_SCHED; PG8_LDA(At, 0, 0); PG8_STAGE(PG8_SA(1, 1), a1 + hstep, voffA);
;             PG8_WAIT_V(8); PG8_WAIT_L(0); PG8_BAR; PG8_MMA(0, 0, At, B0); PG8_MMA(0, 1, At, B1); PG8_BAR; PG8_SCHED;
;             PG8_LDA(At, 0, 1); PG8_STAGE(PG8_SB(0, 0), b2, voffB); PG8_STAGE(PG8_SB(0, 1), b2 + hstep, voffB); PG8_STAGE(PG8_SA(0, 0), a2, voffA);
;             PG8_WAIT_V(8); PG8_WAIT_L(0); PG8_BAR; PG8_MMA(1, 0, At, B0); PG8_MMA(1, 1, At, B1); PG8_BAR; PG8_SCHED;
.LBB0_557:
	ds_read_b128 v[144:147], v155
	ds_read_b128 v[160:163], v155 offset:1024
	ds_read_b128 v[164:167], v155 offset:2048
	ds_read_b128 v[168:171], v155 offset:3072
	ds_read_b128 v[172:175], v156
	ds_read_b128 v[176:179], v156 offset:1024
	ds_read_b128 v[180:183], v156 offset:2048
	ds_read_b128 v[184:187], v156 offset:3072
	s_add_u32 s54, s50, 0xfff80080
	s_addc_u32 s55, s51, -1
	s_cmp_eq_u32 s73, 28
	s_cselect_b32 s57, s10, s55
	s_cselect_b32 s56, s11, s54
	s_cselect_b32 s55, s41, s72
	s_cselect_b32 s54, s43, s49
	s_add_i32 m0, s33, 0xc000
	ds_read_b128 v[188:191], v157
	ds_read_b128 v[192:195], v157 offset:1024
	ds_read_b128 v[196:199], v157 offset:2048
	ds_read_b128 v[200:203], v157 offset:3072
	ds_read_b128 v[204:207], v157 offset:4096
	ds_read_b128 v[208:211], v157 offset:5120
	ds_read_b128 v[212:215], v157 offset:6144
	ds_read_b128 v[216:219], v157 offset:7168
	global_load_lds_dwordx4 v136, s[50:51]
	s_add_i32 m0, s33, 0xe000
	s_nop 0
	global_load_lds_dwordx4 v138, s[50:51]
	s_waitcnt vmcnt(8)
	s_waitcnt lgkmcnt(0)
	s_setprio 1
	s_barrier
	v_mfma_f32_16x16x32_bf16 v[124:127], v[144:147], v[188:191], v[124:127]
	v_mfma_f32_16x16x32_bf16 v[124:127], v[160:163], v[192:195], v[124:127]
	v_mfma_f32_16x16x32_bf16 v[108:111], v[144:147], v[196:199], v[108:111]
	v_mfma_f32_16x16x32_bf16 v[108:111], v[160:163], v[200:203], v[108:111]
	v_mfma_f32_16x16x32_bf16 v[92:95], v[144:147], v[204:207], v[92:95]
	v_mfma_f32_16x16x32_bf16 v[92:95], v[160:163], v[208:211], v[92:95]
	v_mfma_f32_16x16x32_bf16 v[76:79], v[144:147], v[212:215], v[76:79]
	v_mfma_f32_16x16x32_bf16 v[76:79], v[160:163], v[216:219], v[76:79]
	v_mfma_f32_16x16x32_bf16 v[72:75], v[164:167], v[212:215], v[72:75]
	v_mfma_f32_16x16x32_bf16 v[72:75], v[168:171], v[216:219], v[72:75]
	v_mfma_f32_16x16x32_bf16 v[88:91], v[164:167], v[204:207], v[88:91]
	v_mfma_f32_16x16x32_bf16 v[88:91], v[168:171], v[208:211], v[88:91]
	v_mfma_f32_16x16x32_bf16 v[104:107], v[164:167], v[196:199], v[104:107]
	v_mfma_f32_16x16x32_bf16 v[104:107], v[168:171], v[200:203], v[104:107]
	v_mfma_f32_16x16x32_bf16 v[120:123], v[164:167], v[188:191], v[120:123]
	v_mfma_f32_16x16x32_bf16 v[120:123], v[168:171], v[192:195], v[120:123]
	v_mfma_f32_16x16x32_bf16 v[116:119], v[172:175], v[188:191], v[116:119]
	v_mfma_f32_16x16x32_bf16 v[116:119], v[176:179], v[192:195], v[116:119]
	v_mfma_f32_16x16x32_bf16 v[100:103], v[172:175], v[196:199], v[100:103]
	v_mfma_f32_16x16x32_bf16 v[100:103], v[176:179], v[200:203], v[100:103]
	v_mfma_f32_16x16x32_bf16 v[84:87], v[172:175], v[204:207], v[84:87]
	v_mfma_f32_16x16x32_bf16 v[84:87], v[176:179], v[208:211], v[84:87]
	v_mfma_f32_16x16x32_bf16 v[68:71], v[172:175], v[212:215], v[68:71]
	v_mfma_f32_16x16x32_bf16 v[68:71], v[176:179], v[216:219], v[68:71]
	v_mfma_f32_16x16x32_bf16 v[64:67], v[180:183], v[212:215], v[64:67]
	v_mfma_f32_16x16x32_bf16 v[64:67], v[184:187], v[216:219], v[64:67]
	v_mfma_f32_16x16x32_bf16 v[80:83], v[180:183], v[204:207], v[80:83]
	v_mfma_f32_16x16x32_bf16 v[80:83], v[184:187], v[208:211], v[80:83]
	s_setprio 2
	s_barrier
	v_mfma_f32_16x16x32_bf16 v[96:99], v[180:183], v[196:199], v[96:99]
	v_mfma_f32_16x16x32_bf16 v[96:99], v[184:187], v[200:203], v[96:99]
	v_mfma_f32_16x16x32_bf16 v[112:115], v[180:183], v[188:191], v[112:115]
	v_mfma_f32_16x16x32_bf16 v[112:115], v[184:187], v[192:195], v[112:115]
	s_setprio 0
	s_add_i32 s62, s67, s3
	v_lshl_add_u64 v[220:221], s[54:55], 0, v[130:131]
	s_mov_b32 m0, s62
	ds_read_b128 v[188:191], v157 offset:16384
	ds_read_b128 v[192:195], v157 offset:17408
	ds_read_b128 v[196:199], v157 offset:18432
	ds_read_b128 v[200:203], v157 offset:19456
	ds_read_b128 v[204:207], v157 offset:20480
	ds_read_b128 v[208:211], v157 offset:21504
	ds_read_b128 v[212:215], v157 offset:22528
	ds_read_b128 v[216:219], v157 offset:23552
	global_load_lds_dwordx4 v130, s[54:55]
	s_add_i32 m0, s62, 0x2000
	s_add_u32 s62, s54, 0x80000
	v_lshl_add_u64 v[222:223], s[54:55], 0, v[134:135]
	s_addc_u32 s63, s55, 0
	s_add_i32 s74, s70, s3
	global_load_lds_dwordx4 v134, s[54:55]
	s_mov_b32 m0, s74
	v_lshl_add_u64 v[226:227], s[56:57], 0, v[132:133]
	global_load_lds_dwordx4 v130, s[62:63]
	s_add_i32 m0, s74, 0x2000
	s_nop 0
	global_load_lds_dwordx4 v134, s[62:63]
	v_lshl_add_u64 v[224:225], s[56:57], 0, v[128:129]
	s_mov_b32 m0, s33
	s_nop 0
	global_load_lds_dwordx4 v128, s[56:57]
	s_mov_b32 m0, s35
	s_nop 0
	global_load_lds_dwordx4 v132, s[56:57]
	s_waitcnt vmcnt(8)
	s_waitcnt lgkmcnt(0)
	s_setprio 1
	s_barrier
	v_mfma_f32_16x16x32_bf16 v[60:63], v[144:147], v[188:191], v[60:63]
	v_mfma_f32_16x16x32_bf16 v[60:63], v[160:163], v[192:195], v[60:63]
	v_mfma_f32_16x16x32_bf16 v[44:47], v[144:147], v[196:199], v[44:47]
	v_mfma_f32_16x16x32_bf16 v[44:47], v[160:163], v[200:203], v[44:47]
	v_mfma_f32_16x16x32_bf16 v[28:31], v[144:147], v[204:207], v[28:31]
	v_mfma_f32_16x16x32_bf16 v[28:31], v[160:163], v[208:211], v[28:31]
	v_mfma_f32_16x16x32_bf16 v[12:15], v[144:147], v[212:215], v[12:15]
	v_mfma_f32_16x16x32_bf16 v[12:15], v[160:163], v[216:219], v[12:15]
	v_mfma_f32_16x16x32_bf16 v[8:11], v[164:167], v[212:215], v[8:11]
	v_mfma_f32_16x16x32_bf16 v[8:11], v[168:171], v[216:219], v[8:11]
	v_mfma_f32_16x16x32_bf16 v[24:27], v[164:167], v[204:207], v[24:27]
	v_mfma_f32_16x16x32_bf16 v[24:27], v[168:171], v[208:211], v[24:27]
	v_mfma_f32_16x16x32_bf16 v[40:43], v[164:167], v[196:199], v[40:43]
	v_mfma_f32_16x16x32_bf16 v[40:43], v[168:171], v[200:203], v[40:43]
	v_mfma_f32_16x16x32_bf16 v[56:59], v[164:167], v[188:191], v[56:59]
	v_mfma_f32_16x16x32_bf16 v[56:59], v[168:171], v[192:195], v[56:59]
	v_mfma_f32_16x16x32_bf16 v[52:55], v[172:175], v[188:191], v[52:55]
	v_mfma_f32_16x16x32_bf16 v[52:55], v[176:179], v[192:195], v[52:55]
	v_mfma_f32_16x16x32_bf16 v[36:39], v[172:175], v[196:199], v[36:39]
	v_mfma_f32_16x16x32_bf16 v[36:39], v[176:179], v[200:203], v[36:39]
	v_mfma_f32_16x16x32_bf16 v[20:23], v[172:175], v[204:207], v[20:23]
	v_mfma_f32_16x16x32_bf16 v[20:23], v[176:179], v[208:211], v[20:23]
	v_mfma_f32_16x16x32_bf16 v[4:7], v[172:175], v[212:215], v[4:7]
	v_mfma_f32_16x16x32_bf16 v[4:7], v[176:179], v[216:219], v[4:7]
	v_mfma_f32_16x16x32_bf16 v[0:3], v[180:183], v[212:215], v[0:3]
	v_mfma_f32_16x16x32_bf16 v[0:3], v[184:187], v[216:219], v[0:3]
	v_mfma_f32_16x16x32_bf16 v[16:19], v[180:183], v[204:207], v[16:19]
	v_mfma_f32_16x16x32_bf16 v[16:19], v[184:187], v[208:211], v[16:19]
	s_setprio 2
	s_barrier
; #define PG8_STAGE(bufoff, gbase, voff) do { _Pragma("unroll") for (int _i = 0; _i < 2; ++_i) \
;         __builtin_amdgcn_global_load_lds((const unsigned*)((const char*)(gbase) + (voff)[_i]), (PG8_LAS unsigned*)(lds + (bufoff) + ldsw + _i * 8192), 16, 0, 0); } while (0)
; #define PG8_LDA(dst, b, h) do { _Pragma("unroll") for (int m = 0; m < 4; ++m) _Pragma("unroll") for (int k = 0; k < 2; ++k) dst[m][k] = *(const PG8_LAS bf16x8*)(lds + PG8_SA(b, h) + aoff + m * 2048 + k * 1024); } while (0)
; #define PG8_LDB(dst, b, h) do { _Pragma("unroll") for (int n = 0; n < 2; ++n) _Pragma("unroll") for (int k = 0; k < 2; ++k) dst[n][k] = *(const PG8_LAS bf16x8*)(lds + PG8_SB(b, h) + boff + n * 2048 + k * 1024); } while (0)
; #define PG8_MMA(ai, bj, At, Bt) do { __builtin_amdgcn_s_setprio(1); _Pragma("unroll") for (int m = 0; m < 4; ++m) _Pragma("unroll") for (int n = 0; n < 2; ++n) _Pragma("unroll") for (int k = 0; k < 2; ++k) \
;         acc[ai][bj][m][n] = __builtin_amdgcn_mfma_f32_16x16x32_bf16(Bt[n][k], At[m][k], acc[ai][bj][m][n], 0, 0, 0); __builtin_amdgcn_s_setprio(0); } while (0)
; #define PG8_WAIT_V(n) asm volatile("s_waitcnt vmcnt(" #n ")" ::: "memory")
; #define PG8_WAIT_L(n) asm volatile("s_waitcnt lgkmcnt(" #n ")" ::: "memory")
; #define PG8_BAR __builtin_amdgcn_s_barrier()
; #define PG8_SCHED __builtin_amdgcn_sched_barrier(0)
; template <class Epi, class Sched, bool ALIGN_EPI = false, bool SP2 = false>
; __device__ __forceinline__ void gemm_phase(PG8_LAS unsigned char* lds, const Gemm g, const Sched& S, const Epi& E) {
;     ...
;             PG8_WAIT_V(8); PG8_WAIT_L(0); PG8_BAR; PG8_MMA(1, 0, At, B0); PG8_MMA(1, 1, At, B1); PG8_BAR; PG8_SCHED;
;             PG8_LDB(B0, 1, 0); PG8_LDB(B1, 1, 1); PG8_SCHED; PG8_LDA(At, 1, 0); PG8_STAGE(PG8_SA(0, 1), a2 + hstep, voffA);
;             PG8_WAIT_V(8); PG8_WAIT_L(0); PG8_BAR; PG8_MMA(0, 0, At, B0); PG8_MMA(0, 1, At, B1); PG8_BAR; PG8_SCHED;
	v_mfma_f32_16x16x32_bf16 v[32:35], v[180:183], v[196:199], v[32:35]
	v_mfma_f32_16x16x32_bf16 v[32:35], v[184:187], v[200:203], v[32:35]
	v_mfma_f32_16x16x32_bf16 v[48:51], v[180:183], v[188:191], v[48:51]
	v_mfma_f32_16x16x32_bf16 v[48:51], v[184:187], v[192:195], v[48:51]
	s_setprio 0
	s_add_i32 s62, 0, 0x18000
	v_add_u32_e32 v159, s62, v153
	s_add_i32 s63, 0, 0x1c000
	ds_read_b128 v[144:147], v159
	ds_read_b128 v[160:163], v159 offset:1024
	ds_read_b128 v[164:167], v159 offset:2048
	ds_read_b128 v[168:171], v159 offset:3072
	v_add_u32_e32 v159, s63, v153
	ds_read_b128 v[172:175], v159
	ds_read_b128 v[176:179], v159 offset:1024
	ds_read_b128 v[180:183], v159 offset:2048
	ds_read_b128 v[184:187], v159 offset:3072
	s_add_u32 s56, s56, 0x80000
	s_addc_u32 s57, s57, 0
	s_mov_b32 m0, s52
	ds_read_b128 v[188:191], v157 offset:32768
	ds_read_b128 v[192:195], v157 offset:33792
	ds_read_b128 v[196:199], v157 offset:34816
	ds_read_b128 v[200:203], v157 offset:35840
	ds_read_b128 v[204:207], v157 offset:36864
	ds_read_b128 v[208:211], v157 offset:37888
	ds_read_b128 v[212:215], v157 offset:38912
	ds_read_b128 v[216:219], v157 offset:39936
	global_load_lds_dwordx4 v128, s[56:57]
	s_mov_b32 m0, s53
	s_nop 0
	global_load_lds_dwordx4 v132, s[56:57]
	s_waitcnt vmcnt(8)
	s_waitcnt lgkmcnt(0)
	s_setprio 1
	s_barrier
	v_mfma_f32_16x16x32_bf16 v[124:127], v[144:147], v[188:191], v[124:127]
	v_mfma_f32_16x16x32_bf16 v[124:127], v[160:163], v[192:195], v[124:127]
	v_mfma_f32_16x16x32_bf16 v[108:111], v[144:147], v[196:199], v[108:111]
	v_mfma_f32_16x16x32_bf16 v[108:111], v[160:163], v[200:203], v[108:111]
	v_mfma_f32_16x16x32_bf16 v[92:95], v[144:147], v[204:207], v[92:95]
	v_mfma_f32_16x16x32_bf16 v[92:95], v[160:163], v[208:211], v[92:95]
	v_mfma_f32_16x16x32_bf16 v[76:79], v[144:147], v[212:215], v[76:79]
	v_mfma_f32_16x16x32_bf16 v[76:79], v[160:163], v[216:219], v[76:79]
	v_mfma_f32_16x16x32_bf16 v[72:75], v[164:167], v[212:215], v[72:75]
	v_mfma_f32_16x16x32_bf16 v[72:75], v[168:171], v[216:219], v[72:75]
	v_mfma_f32_16x16x32_bf16 v[88:91], v[164:167], v[204:207], v[88:91]
	v_mfma_f32_16x16x32_bf16 v[88:91], v[168:171], v[208:211], v[88:91]
	v_mfma_f32_16x16x32_bf16 v[104:107], v[164:167], v[196:199], v[104:107]
	v_mfma_f32_16x16x32_bf16 v[104:107], v[168:171], v[200:203], v[104:107]
	v_mfma_f32_16x16x32_bf16 v[120:123], v[164:167], v[188:191], v[120:123]
	v_mfma_f32_16x16x32_bf16 v[120:123], v[168:171], v[192:195], v[120:123]
	v_mfma_f32_16x16x32_bf16 v[116:119], v[172:175], v[188:191], v[116:119]
	v_mfma_f32_16x16x32_bf16 v[116:119], v[176:179], v[192:195], v[116:119]
	v_mfma_f32_16x16x32_bf16 v[100:103], v[172:175], v[196:199], v[100:103]
	v_mfma_f32_16x16x32_bf16 v[100:103], v[176:179], v[200:203], v[100:103]
	v_mfma_f32_16x16x32_bf16 v[84:87], v[172:175], v[204:207], v[84:87]
	v_mfma_f32_16x16x32_bf16 v[84:87], v[176:179], v[208:211], v[84:87]
	v_mfma_f32_16x16x32_bf16 v[68:71], v[172:175], v[212:215], v[68:71]
	v_mfma_f32_16x16x32_bf16 v[68:71], v[176:179], v[216:219], v[68:71]
	v_mfma_f32_16x16x32_bf16 v[64:67], v[180:183], v[212:215], v[64:67]
	v_mfma_f32_16x16x32_bf16 v[64:67], v[184:187], v[216:219], v[64:67]
	v_mfma_f32_16x16x32_bf16 v[80:83], v[180:183], v[204:207], v[80:83]
	v_mfma_f32_16x16x32_bf16 v[80:83], v[184:187], v[208:211], v[80:83]
	s_setprio 2
	s_barrier
; #define PG8_STAGE(bufoff, gbase, voff) do { _Pragma("unroll") for (int _i = 0; _i < 2; ++_i) \
;         __builtin_amdgcn_global_load_lds((const unsigned*)((const char*)(gbase) + (voff)[_i]), (PG8_LAS unsigned*)(lds + (bufoff) + ldsw + _i * 8192), 16, 0, 0); } while (0)
; #define PG8_LDA(dst, b, h) do { _Pragma("unroll") for (int m = 0; m < 4; ++m) _Pragma("unroll") for (int k = 0; k < 2; ++k) dst[m][k] = *(const PG8_LAS bf16x8*)(lds + PG8_SA(b, h) + aoff + m * 2048 + k * 1024); } while (0)
; #define PG8_MMA(ai, bj, At, Bt) do { __builtin_amdgcn_s_setprio(1); _Pragma("unroll") for (int m = 0; m < 4; ++m) _Pragma("unroll") for (int n = 0; n < 2; ++n) _Pragma("unroll") for (int k = 0; k < 2; ++k) \
;         acc[ai][bj][m][n] = __builtin_amdgcn_mfma_f32_16x16x32_bf16(Bt[n][k], At[m][k], acc[ai][bj][m][n], 0, 0, 0); __builtin_amdgcn_s_setprio(0); } while (0)
; #define PG8_WAIT_V(n) asm volatile("s_waitcnt vmcnt(" #n ")" ::: "memory")
; #define PG8_WAIT_L(n) asm volatile("s_waitcnt lgkmcnt(" #n ")" ::: "memory")
; #define PG8_BAR __builtin_amdgcn_s_barrier()
; #define PG8_SCHED __builtin_amdgcn_sched_barrier(0)
; template <class Epi, class Sched, bool ALIGN_EPI = false, bool SP2 = false>
; __device__ __forceinline__ void gemm_phase(PG8_LAS unsigned char* lds, const Gemm g, const Sched& S, const Epi& E) {
;     ...
;             PG8_WAIT_V(8); PG8_WAIT_L(0); PG8_BAR; PG8_MMA(0, 0, At, B0); PG8_MMA(0, 1, At, B1); PG8_BAR; PG8_SCHED;
;             PG8_LDA(At, 1, 1); PG8_STAGE(PG8_SB(1, 0), b3, voffB); PG8_STAGE(PG8_SB(1, 1), b3 + hstep, voffB); PG8_STAGE(PG8_SA(1, 0), a3, voffA);
;             PG8_WAIT_V(8); PG8_WAIT_L(0); PG8_BAR; PG8_MMA(1, 0, At, B0); PG8_MMA(1, 1, At, B1); PG8_BAR; PG8_SCHED;
;     ...
;         if constexpr (ALIGN_EPI) { if (wr == 0) PG8_BAR; }
	v_mfma_f32_16x16x32_bf16 v[96:99], v[180:183], v[196:199], v[96:99]
	v_mfma_f32_16x16x32_bf16 v[96:99], v[184:187], v[200:203], v[96:99]
	v_mfma_f32_16x16x32_bf16 v[112:115], v[180:183], v[188:191], v[112:115]
	v_mfma_f32_16x16x32_bf16 v[112:115], v[184:187], v[192:195], v[112:115]
	s_setprio 0
	s_add_i32 s56, s62, s3
	v_lshl_add_u64 v[220:221], v[220:221], 0, s[20:21]
	s_mov_b32 m0, s56
	ds_read_b128 v[188:191], v157 offset:49152
	ds_read_b128 v[192:195], v157 offset:50176
	ds_read_b128 v[196:199], v157 offset:51200
	ds_read_b128 v[200:203], v157 offset:52224
	ds_read_b128 v[204:207], v157 offset:53248
	ds_read_b128 v[208:211], v157 offset:54272
	ds_read_b128 v[212:215], v157 offset:55296
	ds_read_b128 v[216:219], v157 offset:56320
	global_load_lds_dwordx4 v[220:221], off
	s_add_i32 m0, s56, 0x2000
	s_add_u32 s54, s54, 0x80080
	v_lshl_add_u64 v[220:221], v[222:223], 0, s[20:21]
	s_addc_u32 s55, s55, 0
	s_add_i32 s56, s63, s3
	global_load_lds_dwordx4 v[220:221], off
	s_mov_b32 m0, s56
	s_nop 0
	global_load_lds_dwordx4 v130, s[54:55]
	s_add_i32 m0, s56, 0x2000
	s_nop 0
	global_load_lds_dwordx4 v134, s[54:55]
	v_lshl_add_u64 v[220:221], v[224:225], 0, s[20:21]
	s_mov_b32 m0, s64
	s_nop 0
	global_load_lds_dwordx4 v[220:221], off
	v_lshl_add_u64 v[220:221], v[226:227], 0, s[20:21]
	s_mov_b32 m0, s65
	s_nop 0
	global_load_lds_dwordx4 v[220:221], off
	s_waitcnt vmcnt(8)
	s_waitcnt lgkmcnt(0)
	s_setprio 1
	s_barrier
	v_mfma_f32_16x16x32_bf16 v[60:63], v[144:147], v[188:191], v[60:63]
	v_mfma_f32_16x16x32_bf16 v[60:63], v[160:163], v[192:195], v[60:63]
	v_mfma_f32_16x16x32_bf16 v[44:47], v[144:147], v[196:199], v[44:47]
	v_mfma_f32_16x16x32_bf16 v[44:47], v[160:163], v[200:203], v[44:47]
	v_mfma_f32_16x16x32_bf16 v[28:31], v[144:147], v[204:207], v[28:31]
	v_mfma_f32_16x16x32_bf16 v[28:31], v[160:163], v[208:211], v[28:31]
	v_mfma_f32_16x16x32_bf16 v[12:15], v[144:147], v[212:215], v[12:15]
	v_mfma_f32_16x16x32_bf16 v[12:15], v[160:163], v[216:219], v[12:15]
	v_mfma_f32_16x16x32_bf16 v[8:11], v[164:167], v[212:215], v[8:11]
	v_mfma_f32_16x16x32_bf16 v[8:11], v[168:171], v[216:219], v[8:11]
	v_mfma_f32_16x16x32_bf16 v[24:27], v[164:167], v[204:207], v[24:27]
	v_mfma_f32_16x16x32_bf16 v[24:27], v[168:171], v[208:211], v[24:27]
	v_mfma_f32_16x16x32_bf16 v[40:43], v[164:167], v[196:199], v[40:43]
	v_mfma_f32_16x16x32_bf16 v[40:43], v[168:171], v[200:203], v[40:43]
	v_mfma_f32_16x16x32_bf16 v[56:59], v[164:167], v[188:191], v[56:59]
	v_mfma_f32_16x16x32_bf16 v[56:59], v[168:171], v[192:195], v[56:59]
	v_mfma_f32_16x16x32_bf16 v[52:55], v[172:175], v[188:191], v[52:55]
	v_mfma_f32_16x16x32_bf16 v[52:55], v[176:179], v[192:195], v[52:55]
	v_mfma_f32_16x16x32_bf16 v[36:39], v[172:175], v[196:199], v[36:39]
	v_mfma_f32_16x16x32_bf16 v[36:39], v[176:179], v[200:203], v[36:39]
	v_mfma_f32_16x16x32_bf16 v[20:23], v[172:175], v[204:207], v[20:23]
	v_mfma_f32_16x16x32_bf16 v[20:23], v[176:179], v[208:211], v[20:23]
	v_mfma_f32_16x16x32_bf16 v[4:7], v[172:175], v[212:215], v[4:7]
	v_mfma_f32_16x16x32_bf16 v[4:7], v[176:179], v[216:219], v[4:7]
	v_mfma_f32_16x16x32_bf16 v[0:3], v[180:183], v[212:215], v[0:3]
	v_mfma_f32_16x16x32_bf16 v[0:3], v[184:187], v[216:219], v[0:3]
	v_mfma_f32_16x16x32_bf16 v[16:19], v[180:183], v[204:207], v[16:19]
	v_mfma_f32_16x16x32_bf16 v[16:19], v[184:187], v[208:211], v[16:19]
	s_setprio 2
	s_barrier
	v_mfma_f32_16x16x32_bf16 v[32:35], v[180:183], v[196:199], v[32:35]
	v_mfma_f32_16x16x32_bf16 v[32:35], v[184:187], v[200:203], v[32:35]
	v_mfma_f32_16x16x32_bf16 v[48:51], v[180:183], v[188:191], v[48:51]
	v_mfma_f32_16x16x32_bf16 v[48:51], v[184:187], v[192:195], v[48:51]
	s_setprio 0
	s_add_i32 s73, s73, 2
	s_add_u32 s50, s50, 0x100
	s_addc_u32 s51, s51, 0
	s_add_u32 s49, s49, 0x100
	s_addc_u32 s72, s72, 0
	s_cmp_gt_u32 s73, 29
	s_cbranch_scc0 .LBB0_557
	s_and_b64 vcc, exec, s[38:39]
	s_cbranch_vccz .LBB0_560
	s_barrier

; #define PG8_STAGE(bufoff, gbase, voff) do { _Pragma("unroll") for (int _i = 0; _i < 2; ++_i) \
;         __builtin_amdgcn_global_load_lds((const unsigned*)((const char*)(gbase) + (voff)[_i]), (PG8_LAS unsigned*)(lds + (bufoff) + ldsw + _i * 8192), 16, 0, 0); } while (0)
; #define PG8_LDA(dst, b, h) do { _Pragma("unroll") for (int m = 0; m < 4; ++m) _Pragma("unroll") for (int k = 0; k < 2; ++k) dst[m][k] = *(const PG8_LAS bf16x8*)(lds + PG8_SA(b, h) + aoff + m * 2048 + k * 1024); } while (0)
; #define PG8_LDB(dst, b, h) do { _Pragma("unroll") for (int n = 0; n < 2; ++n) _Pragma("unroll") for (int k = 0; k < 2; ++k) dst[n][k] = *(const PG8_LAS bf16x8*)(lds + PG8_SB(b, h) + boff + n * 2048 + k * 1024); } while (0)
; #define PG8_MMA(ai, bj, At, Bt) do { __builtin_amdgcn_s_setprio(1); _Pragma("unroll") for (int m = 0; m < 4; ++m) _Pragma("unroll") for (int n = 0; n < 2; ++n) _Pragma("unroll") for (int k = 0; k < 2; ++k) \
;         acc[ai][bj][m][n] = __builtin_amdgcn_mfma_f32_16x16x32_bf16(Bt[n][k], At[m][k], acc[ai][bj][m][n], 0, 0, 0); __builtin_amdgcn_s_setprio(0); } while (0)
; #define PG8_WAIT_V(n) asm volatile("s_waitcnt vmcnt(" #n ")" ::: "memory")
; #define PG8_WAIT_L(n) asm volatile("s_waitcnt lgkmcnt(" #n ")" ::: "memory")
; template <class Epi, class Sched, bool ALIGN_EPI = false, bool SP2 = false>
; __device__ __forceinline__ void gemm_phase(PG8_LAS unsigned char* lds, const Gemm g, const Sched& S, const Epi& E) {
;     ...
;             const bool last = (t == nt - 2);
;             const char* a1 = cA + (size_t)(t + 1) * kstep;
;             const char* a2 = last ? nA : cA + (size_t)(t + 2) * kstep; const char* b2 = last ? nB : cB + (size_t)(t + 2) * kstep;
;             const char* a3 = a2 + kstep; const char* b3 = b2 + kstep;
;             if (last && has_next) S.a_ready(nxt);
;             if constexpr (SP2) {
;             PG8_LDB(B0, 0, 0); PG8_LDB(B1, 0, 1); PG8_SCHED; PG8_LDA(At, 0, 0); PG8_STAGE(PG8_SA(1, 1), a1 + hstep, voffA);
;             PG8_WAIT_V(8); PG8_WAIT_L(0); PG8_BAR; PG8_MMA(0, 0, At, B0); PG8_MMA(0, 1, At, B1); PG8_BAR; PG8_SCHED;
;             PG8_LDA(At, 0, 1); PG8_STAGE(PG8_SB(0, 0), b2, voffB); PG8_STAGE(PG8_SB(0, 1), b2 + hstep, voffB); PG8_STAGE(PG8_SA(0, 0), a2, voffA);
;             PG8_WAIT_V(8); PG8_WAIT_L(0); PG8_BAR; PG8_MMA(1, 0, At, B0); PG8_MMA(1, 1, At, B1); PG8_BAR; PG8_SCHED;
.LBB0_700:
	ds_read_b128 v[164:167], v155
	ds_read_b128 v[168:171], v155 offset:1024
	ds_read_b128 v[172:175], v155 offset:2048
	ds_read_b128 v[176:179], v155 offset:3072
	ds_read_b128 v[180:183], v157
	ds_read_b128 v[184:187], v157 offset:1024
	ds_read_b128 v[188:191], v157 offset:2048
	ds_read_b128 v[192:195], v157 offset:3072
	s_add_u32 s46, s44, 0xfff80080
	s_addc_u32 s47, s45, -1
	s_cmp_eq_u32 s67, 28
	s_cselect_b32 s49, s10, s47
	s_cselect_b32 s48, s11, s46
	s_cselect_b32 s47, s21, s66
	s_cselect_b32 s46, s37, s65
	s_add_i32 m0, s43, 0xc000
	ds_read_b128 v[196:199], v159
	ds_read_b128 v[200:203], v159 offset:1024
	ds_read_b128 v[204:207], v159 offset:2048
	ds_read_b128 v[208:211], v159 offset:3072
	ds_read_b128 v[212:215], v159 offset:4096
	ds_read_b128 v[216:219], v159 offset:5120
	ds_read_b128 v[220:223], v159 offset:6144
	ds_read_b128 v[224:227], v159 offset:7168
	global_load_lds_dwordx4 v138, s[44:45]
	s_add_i32 m0, s43, 0xe000
	s_nop 0
	global_load_lds_dwordx4 v140, s[44:45]
	s_waitcnt vmcnt(8)
	s_waitcnt lgkmcnt(0)
	s_setprio 1
	s_barrier
	v_mfma_f32_16x16x32_bf16 v[124:127], v[164:167], v[196:199], v[124:127]
	v_mfma_f32_16x16x32_bf16 v[124:127], v[168:171], v[200:203], v[124:127]
	v_mfma_f32_16x16x32_bf16 v[108:111], v[164:167], v[204:207], v[108:111]
	v_mfma_f32_16x16x32_bf16 v[108:111], v[168:171], v[208:211], v[108:111]
	v_mfma_f32_16x16x32_bf16 v[92:95], v[164:167], v[212:215], v[92:95]
	v_mfma_f32_16x16x32_bf16 v[92:95], v[168:171], v[216:219], v[92:95]
	v_mfma_f32_16x16x32_bf16 v[76:79], v[164:167], v[220:223], v[76:79]
	v_mfma_f32_16x16x32_bf16 v[76:79], v[168:171], v[224:227], v[76:79]
	v_mfma_f32_16x16x32_bf16 v[72:75], v[172:175], v[220:223], v[72:75]
	v_mfma_f32_16x16x32_bf16 v[72:75], v[176:179], v[224:227], v[72:75]
	v_mfma_f32_16x16x32_bf16 v[88:91], v[172:175], v[212:215], v[88:91]
	v_mfma_f32_16x16x32_bf16 v[88:91], v[176:179], v[216:219], v[88:91]
	v_mfma_f32_16x16x32_bf16 v[104:107], v[172:175], v[204:207], v[104:107]
	v_mfma_f32_16x16x32_bf16 v[104:107], v[176:179], v[208:211], v[104:107]
	v_mfma_f32_16x16x32_bf16 v[120:123], v[172:175], v[196:199], v[120:123]
	v_mfma_f32_16x16x32_bf16 v[120:123], v[176:179], v[200:203], v[120:123]
	v_mfma_f32_16x16x32_bf16 v[116:119], v[180:183], v[196:199], v[116:119]
	v_mfma_f32_16x16x32_bf16 v[116:119], v[184:187], v[200:203], v[116:119]
	v_mfma_f32_16x16x32_bf16 v[100:103], v[180:183], v[204:207], v[100:103]
	v_mfma_f32_16x16x32_bf16 v[100:103], v[184:187], v[208:211], v[100:103]
	v_mfma_f32_16x16x32_bf16 v[84:87], v[180:183], v[212:215], v[84:87]
	v_mfma_f32_16x16x32_bf16 v[84:87], v[184:187], v[216:219], v[84:87]
	v_mfma_f32_16x16x32_bf16 v[68:71], v[180:183], v[220:223], v[68:71]
	v_mfma_f32_16x16x32_bf16 v[68:71], v[184:187], v[224:227], v[68:71]
	v_mfma_f32_16x16x32_bf16 v[64:67], v[188:191], v[220:223], v[64:67]
	v_mfma_f32_16x16x32_bf16 v[64:67], v[192:195], v[224:227], v[64:67]
	v_mfma_f32_16x16x32_bf16 v[80:83], v[188:191], v[212:215], v[80:83]
	v_mfma_f32_16x16x32_bf16 v[80:83], v[192:195], v[216:219], v[80:83]
	s_setprio 2
	s_barrier
	v_mfma_f32_16x16x32_bf16 v[96:99], v[188:191], v[204:207], v[96:99]
	v_mfma_f32_16x16x32_bf16 v[96:99], v[192:195], v[208:211], v[96:99]
	v_mfma_f32_16x16x32_bf16 v[112:115], v[188:191], v[196:199], v[112:115]
	v_mfma_f32_16x16x32_bf16 v[112:115], v[192:195], v[200:203], v[112:115]
	s_setprio 0
	s_add_i32 s62, s58, s3
	v_lshl_add_u64 v[228:229], s[46:47], 0, v[130:131]
	s_mov_b32 m0, s62
	ds_read_b128 v[196:199], v159 offset:16384
	ds_read_b128 v[200:203], v159 offset:17408
	ds_read_b128 v[204:207], v159 offset:18432
	ds_read_b128 v[208:211], v159 offset:19456
	ds_read_b128 v[212:215], v159 offset:20480
	ds_read_b128 v[216:219], v159 offset:21504
	ds_read_b128 v[220:223], v159 offset:22528
	ds_read_b128 v[224:227], v159 offset:23552
	global_load_lds_dwordx4 v130, s[46:47]
	s_add_i32 m0, s62, 0x2000
	s_add_u32 s62, s46, 0x80000
	v_lshl_add_u64 v[230:231], s[46:47], 0, v[134:135]
	s_addc_u32 s63, s47, 0
	s_add_i32 s68, s59, s3
	global_load_lds_dwordx4 v134, s[46:47]
	s_mov_b32 m0, s68
	v_lshl_add_u64 v[234:235], s[48:49], 0, v[132:133]
	global_load_lds_dwordx4 v130, s[62:63]
	s_add_i32 m0, s68, 0x2000
	s_nop 0
	global_load_lds_dwordx4 v134, s[62:63]
	v_lshl_add_u64 v[232:233], s[48:49], 0, v[128:129]
	s_mov_b32 m0, s43
	s_nop 0
	global_load_lds_dwordx4 v128, s[48:49]
	s_mov_b32 m0, s50
	s_nop 0
	global_load_lds_dwordx4 v132, s[48:49]
	s_waitcnt vmcnt(8)
	s_waitcnt lgkmcnt(0)
	s_setprio 1
	s_barrier
	v_mfma_f32_16x16x32_bf16 v[60:63], v[164:167], v[196:199], v[60:63]
	v_mfma_f32_16x16x32_bf16 v[60:63], v[168:171], v[200:203], v[60:63]
	v_mfma_f32_16x16x32_bf16 v[44:47], v[164:167], v[204:207], v[44:47]
	v_mfma_f32_16x16x32_bf16 v[44:47], v[168:171], v[208:211], v[44:47]
	v_mfma_f32_16x16x32_bf16 v[28:31], v[164:167], v[212:215], v[28:31]
	v_mfma_f32_16x16x32_bf16 v[28:31], v[168:171], v[216:219], v[28:31]
	v_mfma_f32_16x16x32_bf16 v[12:15], v[164:167], v[220:223], v[12:15]
	v_mfma_f32_16x16x32_bf16 v[12:15], v[168:171], v[224:227], v[12:15]
	v_mfma_f32_16x16x32_bf16 v[8:11], v[172:175], v[220:223], v[8:11]
	v_mfma_f32_16x16x32_bf16 v[8:11], v[176:179], v[224:227], v[8:11]
	v_mfma_f32_16x16x32_bf16 v[24:27], v[172:175], v[212:215], v[24:27]
	v_mfma_f32_16x16x32_bf16 v[24:27], v[176:179], v[216:219], v[24:27]
	v_mfma_f32_16x16x32_bf16 v[40:43], v[172:175], v[204:207], v[40:43]
	v_mfma_f32_16x16x32_bf16 v[40:43], v[176:179], v[208:211], v[40:43]
	v_mfma_f32_16x16x32_bf16 v[56:59], v[172:175], v[196:199], v[56:59]
	v_mfma_f32_16x16x32_bf16 v[56:59], v[176:179], v[200:203], v[56:59]
	v_mfma_f32_16x16x32_bf16 v[52:55], v[180:183], v[196:199], v[52:55]
	v_mfma_f32_16x16x32_bf16 v[52:55], v[184:187], v[200:203], v[52:55]
	v_mfma_f32_16x16x32_bf16 v[36:39], v[180:183], v[204:207], v[36:39]
	v_mfma_f32_16x16x32_bf16 v[36:39], v[184:187], v[208:211], v[36:39]
	v_mfma_f32_16x16x32_bf16 v[20:23], v[180:183], v[212:215], v[20:23]
	v_mfma_f32_16x16x32_bf16 v[20:23], v[184:187], v[216:219], v[20:23]
	v_mfma_f32_16x16x32_bf16 v[4:7], v[180:183], v[220:223], v[4:7]
	v_mfma_f32_16x16x32_bf16 v[4:7], v[184:187], v[224:227], v[4:7]
	v_mfma_f32_16x16x32_bf16 v[0:3], v[188:191], v[220:223], v[0:3]
	v_mfma_f32_16x16x32_bf16 v[0:3], v[192:195], v[224:227], v[0:3]
	v_mfma_f32_16x16x32_bf16 v[16:19], v[188:191], v[212:215], v[16:19]
	v_mfma_f32_16x16x32_bf16 v[16:19], v[192:195], v[216:219], v[16:19]
	s_setprio 2
	s_barrier
; #define PG8_STAGE(bufoff, gbase, voff) do { _Pragma("unroll") for (int _i = 0; _i < 2; ++_i) \
;         __builtin_amdgcn_global_load_lds((const unsigned*)((const char*)(gbase) + (voff)[_i]), (PG8_LAS unsigned*)(lds + (bufoff) + ldsw + _i * 8192), 16, 0, 0); } while (0)
; #define PG8_LDA(dst, b, h) do { _Pragma("unroll") for (int m = 0; m < 4; ++m) _Pragma("unroll") for (int k = 0; k < 2; ++k) dst[m][k] = *(const PG8_LAS bf16x8*)(lds + PG8_SA(b, h) + aoff + m * 2048 + k * 1024); } while (0)
; #define PG8_LDB(dst, b, h) do { _Pragma("unroll") for (int n = 0; n < 2; ++n) _Pragma("unroll") for (int k = 0; k < 2; ++k) dst[n][k] = *(const PG8_LAS bf16x8*)(lds + PG8_SB(b, h) + boff + n * 2048 + k * 1024); } while (0)
; #define PG8_MMA(ai, bj, At, Bt) do { __builtin_amdgcn_s_setprio(1); _Pragma("unroll") for (int m = 0; m < 4; ++m) _Pragma("unroll") for (int n = 0; n < 2; ++n) _Pragma("unroll") for (int k = 0; k < 2; ++k) \
;         acc[ai][bj][m][n] = __builtin_amdgcn_mfma_f32_16x16x32_bf16(Bt[n][k], At[m][k], acc[ai][bj][m][n], 0, 0, 0); __builtin_amdgcn_s_setprio(0); } while (0)
; #define PG8_WAIT_V(n) asm volatile("s_waitcnt vmcnt(" #n ")" ::: "memory")
; #define PG8_WAIT_L(n) asm volatile("s_waitcnt lgkmcnt(" #n ")" ::: "memory")
; #define PG8_BAR __builtin_amdgcn_s_barrier()
; #define PG8_SCHED __builtin_amdgcn_sched_barrier(0)
; template <class Epi, class Sched, bool ALIGN_EPI = false, bool SP2 = false>
; __device__ __forceinline__ void gemm_phase(PG8_LAS unsigned char* lds, const Gemm g, const Sched& S, const Epi& E) {
;     ...
;             PG8_WAIT_V(8); PG8_WAIT_L(0); PG8_BAR; PG8_MMA(1, 0, At, B0); PG8_MMA(1, 1, At, B1); PG8_BAR; PG8_SCHED;
;             PG8_LDB(B0, 1, 0); PG8_LDB(B1, 1, 1); PG8_SCHED; PG8_LDA(At, 1, 0); PG8_STAGE(PG8_SA(0, 1), a2 + hstep, voffA);
;             PG8_WAIT_V(8); PG8_WAIT_L(0); PG8_BAR; PG8_MMA(0, 0, At, B0); PG8_MMA(0, 1, At, B1); PG8_BAR; PG8_SCHED;
	v_mfma_f32_16x16x32_bf16 v[32:35], v[188:191], v[204:207], v[32:35]
	v_mfma_f32_16x16x32_bf16 v[32:35], v[192:195], v[208:211], v[32:35]
	v_mfma_f32_16x16x32_bf16 v[48:51], v[188:191], v[196:199], v[48:51]
	v_mfma_f32_16x16x32_bf16 v[48:51], v[192:195], v[200:203], v[48:51]
	s_setprio 0
	s_add_i32 s62, 0, 0x18000
	v_add_u32_e32 v161, s62, v147
	s_add_i32 s63, 0, 0x1c000
	ds_read_b128 v[164:167], v161
	ds_read_b128 v[168:171], v161 offset:1024
	ds_read_b128 v[172:175], v161 offset:2048
	ds_read_b128 v[176:179], v161 offset:3072
	v_add_u32_e32 v161, s63, v147
	ds_read_b128 v[180:183], v161
	ds_read_b128 v[184:187], v161 offset:1024
	ds_read_b128 v[188:191], v161 offset:2048
	ds_read_b128 v[192:195], v161 offset:3072
	s_add_u32 s48, s48, 0x80000
	s_addc_u32 s49, s49, 0
	s_mov_b32 m0, s51
	ds_read_b128 v[196:199], v159 offset:32768
	ds_read_b128 v[200:203], v159 offset:33792
	ds_read_b128 v[204:207], v159 offset:34816
	ds_read_b128 v[208:211], v159 offset:35840
	ds_read_b128 v[212:215], v159 offset:36864
	ds_read_b128 v[216:219], v159 offset:37888
	ds_read_b128 v[220:223], v159 offset:38912
	ds_read_b128 v[224:227], v159 offset:39936
	global_load_lds_dwordx4 v128, s[48:49]
	s_mov_b32 m0, s52
	s_nop 0
	global_load_lds_dwordx4 v132, s[48:49]
	s_waitcnt vmcnt(8)
	s_waitcnt lgkmcnt(0)
	s_setprio 1
	s_barrier
	v_mfma_f32_16x16x32_bf16 v[124:127], v[164:167], v[196:199], v[124:127]
	v_mfma_f32_16x16x32_bf16 v[124:127], v[168:171], v[200:203], v[124:127]
	v_mfma_f32_16x16x32_bf16 v[108:111], v[164:167], v[204:207], v[108:111]
	v_mfma_f32_16x16x32_bf16 v[108:111], v[168:171], v[208:211], v[108:111]
	v_mfma_f32_16x16x32_bf16 v[92:95], v[164:167], v[212:215], v[92:95]
	v_mfma_f32_16x16x32_bf16 v[92:95], v[168:171], v[216:219], v[92:95]
	v_mfma_f32_16x16x32_bf16 v[76:79], v[164:167], v[220:223], v[76:79]
	v_mfma_f32_16x16x32_bf16 v[76:79], v[168:171], v[224:227], v[76:79]
	v_mfma_f32_16x16x32_bf16 v[72:75], v[172:175], v[220:223], v[72:75]
	v_mfma_f32_16x16x32_bf16 v[72:75], v[176:179], v[224:227], v[72:75]
	v_mfma_f32_16x16x32_bf16 v[88:91], v[172:175], v[212:215], v[88:91]
	v_mfma_f32_16x16x32_bf16 v[88:91], v[176:179], v[216:219], v[88:91]
	v_mfma_f32_16x16x32_bf16 v[104:107], v[172:175], v[204:207], v[104:107]
	v_mfma_f32_16x16x32_bf16 v[104:107], v[176:179], v[208:211], v[104:107]
	v_mfma_f32_16x16x32_bf16 v[120:123], v[172:175], v[196:199], v[120:123]
	v_mfma_f32_16x16x32_bf16 v[120:123], v[176:179], v[200:203], v[120:123]
	v_mfma_f32_16x16x32_bf16 v[116:119], v[180:183], v[196:199], v[116:119]
	v_mfma_f32_16x16x32_bf16 v[116:119], v[184:187], v[200:203], v[116:119]
	v_mfma_f32_16x16x32_bf16 v[100:103], v[180:183], v[204:207], v[100:103]
	v_mfma_f32_16x16x32_bf16 v[100:103], v[184:187], v[208:211], v[100:103]
	v_mfma_f32_16x16x32_bf16 v[84:87], v[180:183], v[212:215], v[84:87]
	v_mfma_f32_16x16x32_bf16 v[84:87], v[184:187], v[216:219], v[84:87]
	v_mfma_f32_16x16x32_bf16 v[68:71], v[180:183], v[220:223], v[68:71]
	v_mfma_f32_16x16x32_bf16 v[68:71], v[184:187], v[224:227], v[68:71]
	v_mfma_f32_16x16x32_bf16 v[64:67], v[188:191], v[220:223], v[64:67]
	v_mfma_f32_16x16x32_bf16 v[64:67], v[192:195], v[224:227], v[64:67]
	v_mfma_f32_16x16x32_bf16 v[80:83], v[188:191], v[212:215], v[80:83]
	v_mfma_f32_16x16x32_bf16 v[80:83], v[192:195], v[216:219], v[80:83]
	s_setprio 2
	s_barrier
; #define PG8_STAGE(bufoff, gbase, voff) do { _Pragma("unroll") for (int _i = 0; _i < 2; ++_i) \
;         __builtin_amdgcn_global_load_lds((const unsigned*)((const char*)(gbase) + (voff)[_i]), (PG8_LAS unsigned*)(lds + (bufoff) + ldsw + _i * 8192), 16, 0, 0); } while (0)
; #define PG8_LDA(dst, b, h) do { _Pragma("unroll") for (int m = 0; m < 4; ++m) _Pragma("unroll") for (int k = 0; k < 2; ++k) dst[m][k] = *(const PG8_LAS bf16x8*)(lds + PG8_SA(b, h) + aoff + m * 2048 + k * 1024); } while (0)
; #define PG8_MMA(ai, bj, At, Bt) do { __builtin_amdgcn_s_setprio(1); _Pragma("unroll") for (int m = 0; m < 4; ++m) _Pragma("unroll") for (int n = 0; n < 2; ++n) _Pragma("unroll") for (int k = 0; k < 2; ++k) \
;         acc[ai][bj][m][n] = __builtin_amdgcn_mfma_f32_16x16x32_bf16(Bt[n][k], At[m][k], acc[ai][bj][m][n], 0, 0, 0); __builtin_amdgcn_s_setprio(0); } while (0)
; #define PG8_WAIT_V(n) asm volatile("s_waitcnt vmcnt(" #n ")" ::: "memory")
; #define PG8_WAIT_L(n) asm volatile("s_waitcnt lgkmcnt(" #n ")" ::: "memory")
; #define PG8_BAR __builtin_amdgcn_s_barrier()
; #define PG8_SCHED __builtin_amdgcn_sched_barrier(0)
; template <class Epi, class Sched, bool ALIGN_EPI = false, bool SP2 = false>
; __device__ __forceinline__ void gemm_phase(PG8_LAS unsigned char* lds, const Gemm g, const Sched& S, const Epi& E) {
;     ...
;             PG8_WAIT_V(8); PG8_WAIT_L(0); PG8_BAR; PG8_MMA(0, 0, At, B0); PG8_MMA(0, 1, At, B1); PG8_BAR; PG8_SCHED;
;             PG8_LDA(At, 1, 1); PG8_STAGE(PG8_SB(1, 0), b3, voffB); PG8_STAGE(PG8_SB(1, 1), b3 + hstep, voffB); PG8_STAGE(PG8_SA(1, 0), a3, voffA);
;             PG8_WAIT_V(8); PG8_WAIT_L(0); PG8_BAR; PG8_MMA(1, 0, At, B0); PG8_MMA(1, 1, At, B1); PG8_BAR; PG8_SCHED;
;     ...
;         if constexpr (ALIGN_EPI) { if (wr == 0) PG8_BAR; }
	v_mfma_f32_16x16x32_bf16 v[96:99], v[188:191], v[204:207], v[96:99]
	v_mfma_f32_16x16x32_bf16 v[96:99], v[192:195], v[208:211], v[96:99]
	v_mfma_f32_16x16x32_bf16 v[112:115], v[188:191], v[196:199], v[112:115]
	v_mfma_f32_16x16x32_bf16 v[112:115], v[192:195], v[200:203], v[112:115]
	s_setprio 0
	s_add_i32 s48, s62, s3
	v_lshl_add_u64 v[228:229], v[228:229], 0, s[8:9]
	s_mov_b32 m0, s48
	ds_read_b128 v[196:199], v159 offset:49152
	ds_read_b128 v[200:203], v159 offset:50176
	ds_read_b128 v[204:207], v159 offset:51200
	ds_read_b128 v[208:211], v159 offset:52224
	ds_read_b128 v[212:215], v159 offset:53248
	ds_read_b128 v[216:219], v159 offset:54272
	ds_read_b128 v[220:223], v159 offset:55296
	ds_read_b128 v[224:227], v159 offset:56320
	global_load_lds_dwordx4 v[228:229], off
	s_add_i32 m0, s48, 0x2000
	s_add_u32 s46, s46, 0x80080
	v_lshl_add_u64 v[228:229], v[230:231], 0, s[8:9]
	s_addc_u32 s47, s47, 0
	s_add_i32 s48, s63, s3
	global_load_lds_dwordx4 v[228:229], off
	s_mov_b32 m0, s48
	s_nop 0
	global_load_lds_dwordx4 v130, s[46:47]
	s_add_i32 m0, s48, 0x2000
	s_nop 0
	global_load_lds_dwordx4 v134, s[46:47]
	v_lshl_add_u64 v[228:229], v[232:233], 0, s[8:9]
	s_mov_b32 m0, s55
	s_nop 0
	global_load_lds_dwordx4 v[228:229], off
	v_lshl_add_u64 v[228:229], v[234:235], 0, s[8:9]
	s_mov_b32 m0, s56
	s_nop 0
	global_load_lds_dwordx4 v[228:229], off
	s_waitcnt vmcnt(8)
	s_waitcnt lgkmcnt(0)
	s_setprio 1
	s_barrier
	v_mfma_f32_16x16x32_bf16 v[60:63], v[164:167], v[196:199], v[60:63]
	v_mfma_f32_16x16x32_bf16 v[60:63], v[168:171], v[200:203], v[60:63]
	v_mfma_f32_16x16x32_bf16 v[44:47], v[164:167], v[204:207], v[44:47]
	v_mfma_f32_16x16x32_bf16 v[44:47], v[168:171], v[208:211], v[44:47]
	v_mfma_f32_16x16x32_bf16 v[28:31], v[164:167], v[212:215], v[28:31]
	v_mfma_f32_16x16x32_bf16 v[28:31], v[168:171], v[216:219], v[28:31]
	v_mfma_f32_16x16x32_bf16 v[12:15], v[164:167], v[220:223], v[12:15]
	v_mfma_f32_16x16x32_bf16 v[12:15], v[168:171], v[224:227], v[12:15]
	v_mfma_f32_16x16x32_bf16 v[8:11], v[172:175], v[220:223], v[8:11]
	v_mfma_f32_16x16x32_bf16 v[8:11], v[176:179], v[224:227], v[8:11]
	v_mfma_f32_16x16x32_bf16 v[24:27], v[172:175], v[212:215], v[24:27]
	v_mfma_f32_16x16x32_bf16 v[24:27], v[176:179], v[216:219], v[24:27]
	v_mfma_f32_16x16x32_bf16 v[40:43], v[172:175], v[204:207], v[40:43]
	v_mfma_f32_16x16x32_bf16 v[40:43], v[176:179], v[208:211], v[40:43]
	v_mfma_f32_16x16x32_bf16 v[56:59], v[172:175], v[196:199], v[56:59]
	v_mfma_f32_16x16x32_bf16 v[56:59], v[176:179], v[200:203], v[56:59]
	v_mfma_f32_16x16x32_bf16 v[52:55], v[180:183], v[196:199], v[52:55]
	v_mfma_f32_16x16x32_bf16 v[52:55], v[184:187], v[200:203], v[52:55]
	v_mfma_f32_16x16x32_bf16 v[36:39], v[180:183], v[204:207], v[36:39]
	v_mfma_f32_16x16x32_bf16 v[36:39], v[184:187], v[208:211], v[36:39]
	v_mfma_f32_16x16x32_bf16 v[20:23], v[180:183], v[212:215], v[20:23]
	v_mfma_f32_16x16x32_bf16 v[20:23], v[184:187], v[216:219], v[20:23]
	v_mfma_f32_16x16x32_bf16 v[4:7], v[180:183], v[220:223], v[4:7]
	v_mfma_f32_16x16x32_bf16 v[4:7], v[184:187], v[224:227], v[4:7]
	v_mfma_f32_16x16x32_bf16 v[0:3], v[188:191], v[220:223], v[0:3]
	v_mfma_f32_16x16x32_bf16 v[0:3], v[192:195], v[224:227], v[0:3]
	v_mfma_f32_16x16x32_bf16 v[16:19], v[188:191], v[212:215], v[16:19]
	v_mfma_f32_16x16x32_bf16 v[16:19], v[192:195], v[216:219], v[16:19]
	s_setprio 2
	s_barrier
	v_mfma_f32_16x16x32_bf16 v[32:35], v[188:191], v[204:207], v[32:35]
	v_mfma_f32_16x16x32_bf16 v[32:35], v[192:195], v[208:211], v[32:35]
	v_mfma_f32_16x16x32_bf16 v[48:51], v[188:191], v[196:199], v[48:51]
	v_mfma_f32_16x16x32_bf16 v[48:51], v[192:195], v[200:203], v[48:51]
	s_setprio 0
	s_add_i32 s67, s67, 2
	s_add_u32 s44, s44, 0x100
	s_addc_u32 s45, s45, 0
	s_add_u32 s65, s65, 0x100
	s_addc_u32 s66, s66, 0
	s_cmp_gt_u32 s67, 29
	s_cbranch_scc0 .LBB0_700
	s_and_b64 vcc, exec, s[12:13]
	s_cbranch_vccz .LBB0_703
	s_barrier

; #define PG8_STAGE(bufoff, gbase, voff) do { _Pragma("unroll") for (int _i = 0; _i < 2; ++_i) \
;         __builtin_amdgcn_global_load_lds((const unsigned*)((const char*)(gbase) + (voff)[_i]), (PG8_LAS unsigned*)(lds + (bufoff) + ldsw + _i * 8192), 16, 0, 0); } while (0)
; #define PG8_LDA(dst, b, h) do { _Pragma("unroll") for (int m = 0; m < 4; ++m) _Pragma("unroll") for (int k = 0; k < 2; ++k) dst[m][k] = *(const PG8_LAS bf16x8*)(lds + PG8_SA(b, h) + aoff + m * 2048 + k * 1024); } while (0)
; #define PG8_LDB(dst, b, h) do { _Pragma("unroll") for (int n = 0; n < 2; ++n) _Pragma("unroll") for (int k = 0; k < 2; ++k) dst[n][k] = *(const PG8_LAS bf16x8*)(lds + PG8_SB(b, h) + boff + n * 2048 + k * 1024); } while (0)
; #define PG8_MMA(ai, bj, At, Bt) do { __builtin_amdgcn_s_setprio(1); _Pragma("unroll") for (int m = 0; m < 4; ++m) _Pragma("unroll") for (int n = 0; n < 2; ++n) _Pragma("unroll") for (int k = 0; k < 2; ++k) \
;         acc[ai][bj][m][n] = __builtin_amdgcn_mfma_f32_16x16x32_bf16(Bt[n][k], At[m][k], acc[ai][bj][m][n], 0, 0, 0); __builtin_amdgcn_s_setprio(0); } while (0)
; #define PG8_WAIT_V(n) asm volatile("s_waitcnt vmcnt(" #n ")" ::: "memory")
; #define PG8_WAIT_L(n) asm volatile("s_waitcnt lgkmcnt(" #n ")" ::: "memory")
; template <class Epi, class Sched, bool ALIGN_EPI = false, bool SP2 = false>
; __device__ __forceinline__ void gemm_phase(PG8_LAS unsigned char* lds, const Gemm g, const Sched& S, const Epi& E) {
;     ...
;             const bool last = (t == nt - 2);
;             const char* a1 = cA + (size_t)(t + 1) * kstep;
;             const char* a2 = last ? nA : cA + (size_t)(t + 2) * kstep; const char* b2 = last ? nB : cB + (size_t)(t + 2) * kstep;
;             const char* a3 = a2 + kstep; const char* b3 = b2 + kstep;
;             if (last && has_next) S.a_ready(nxt);
;             if constexpr (SP2) {
;             PG8_LDB(B0, 0, 0); PG8_LDB(B1, 0, 1); PG8_SCHED; PG8_LDA(At, 0, 0); PG8_STAGE(PG8_SA(1, 1), a1 + hstep, voffA);
;             PG8_WAIT_V(8); PG8_WAIT_L(0); PG8_BAR; PG8_MMA(0, 0, At, B0); PG8_MMA(0, 1, At, B1); PG8_BAR; PG8_SCHED;
;             PG8_LDA(At, 0, 1); PG8_STAGE(PG8_SB(0, 0), b2, voffB); PG8_STAGE(PG8_SB(0, 1), b2 + hstep, voffB); PG8_STAGE(PG8_SA(0, 0), a2, voffA);
;             PG8_WAIT_V(8); PG8_WAIT_L(0); PG8_BAR; PG8_MMA(1, 0, At, B0); PG8_MMA(1, 1, At, B1); PG8_BAR; PG8_SCHED;
.LBB0_779:
	ds_read_b128 v[144:147], v155
	ds_read_b128 v[160:163], v155 offset:1024
	ds_read_b128 v[164:167], v155 offset:2048
	ds_read_b128 v[168:171], v155 offset:3072
	ds_read_b128 v[172:175], v156
	ds_read_b128 v[176:179], v156 offset:1024
	ds_read_b128 v[180:183], v156 offset:2048
	ds_read_b128 v[184:187], v156 offset:3072
	s_add_u32 s40, s38, 0xffea0080
	s_addc_u32 s41, s39, -1
	s_cmpk_eq_i32 s58, 0x54
	s_cselect_b32 s43, s7, s41
	s_cselect_b32 s42, s6, s40
	s_cselect_b32 s41, s37, s57
	s_cselect_b32 s40, s36, s11
	s_add_i32 m0, s33, 0xc000
	ds_read_b128 v[188:191], v157
	ds_read_b128 v[192:195], v157 offset:1024
	ds_read_b128 v[196:199], v157 offset:2048
	ds_read_b128 v[200:203], v157 offset:3072
	ds_read_b128 v[204:207], v157 offset:4096
	ds_read_b128 v[208:211], v157 offset:5120
	ds_read_b128 v[212:215], v157 offset:6144
	ds_read_b128 v[216:219], v157 offset:7168
	global_load_lds_dwordx4 v136, s[38:39]
	s_add_i32 m0, s33, 0xe000
	s_nop 0
	global_load_lds_dwordx4 v138, s[38:39]
	s_waitcnt vmcnt(8)
	s_waitcnt lgkmcnt(0)
	s_setprio 1
	s_barrier
	v_mfma_f32_16x16x32_bf16 v[124:127], v[144:147], v[188:191], v[124:127]
	v_mfma_f32_16x16x32_bf16 v[124:127], v[160:163], v[192:195], v[124:127]
	v_mfma_f32_16x16x32_bf16 v[108:111], v[144:147], v[196:199], v[108:111]
	v_mfma_f32_16x16x32_bf16 v[108:111], v[160:163], v[200:203], v[108:111]
	v_mfma_f32_16x16x32_bf16 v[92:95], v[144:147], v[204:207], v[92:95]
	v_mfma_f32_16x16x32_bf16 v[92:95], v[160:163], v[208:211], v[92:95]
	v_mfma_f32_16x16x32_bf16 v[76:79], v[144:147], v[212:215], v[76:79]
	v_mfma_f32_16x16x32_bf16 v[76:79], v[160:163], v[216:219], v[76:79]
	v_mfma_f32_16x16x32_bf16 v[72:75], v[164:167], v[212:215], v[72:75]
	v_mfma_f32_16x16x32_bf16 v[72:75], v[168:171], v[216:219], v[72:75]
	v_mfma_f32_16x16x32_bf16 v[88:91], v[164:167], v[204:207], v[88:91]
	v_mfma_f32_16x16x32_bf16 v[88:91], v[168:171], v[208:211], v[88:91]
	v_mfma_f32_16x16x32_bf16 v[104:107], v[164:167], v[196:199], v[104:107]
	v_mfma_f32_16x16x32_bf16 v[104:107], v[168:171], v[200:203], v[104:107]
	v_mfma_f32_16x16x32_bf16 v[120:123], v[164:167], v[188:191], v[120:123]
	v_mfma_f32_16x16x32_bf16 v[120:123], v[168:171], v[192:195], v[120:123]
	v_mfma_f32_16x16x32_bf16 v[116:119], v[172:175], v[188:191], v[116:119]
	v_mfma_f32_16x16x32_bf16 v[116:119], v[176:179], v[192:195], v[116:119]
	v_mfma_f32_16x16x32_bf16 v[100:103], v[172:175], v[196:199], v[100:103]
	v_mfma_f32_16x16x32_bf16 v[100:103], v[176:179], v[200:203], v[100:103]
	v_mfma_f32_16x16x32_bf16 v[84:87], v[172:175], v[204:207], v[84:87]
	v_mfma_f32_16x16x32_bf16 v[84:87], v[176:179], v[208:211], v[84:87]
	v_mfma_f32_16x16x32_bf16 v[68:71], v[172:175], v[212:215], v[68:71]
	v_mfma_f32_16x16x32_bf16 v[68:71], v[176:179], v[216:219], v[68:71]
	v_mfma_f32_16x16x32_bf16 v[64:67], v[180:183], v[212:215], v[64:67]
	v_mfma_f32_16x16x32_bf16 v[64:67], v[184:187], v[216:219], v[64:67]
	v_mfma_f32_16x16x32_bf16 v[80:83], v[180:183], v[204:207], v[80:83]
	v_mfma_f32_16x16x32_bf16 v[80:83], v[184:187], v[208:211], v[80:83]
	s_setprio 2
	s_barrier
	v_mfma_f32_16x16x32_bf16 v[96:99], v[180:183], v[196:199], v[96:99]
	v_mfma_f32_16x16x32_bf16 v[96:99], v[184:187], v[200:203], v[96:99]
	v_mfma_f32_16x16x32_bf16 v[112:115], v[180:183], v[188:191], v[112:115]
	v_mfma_f32_16x16x32_bf16 v[112:115], v[184:187], v[192:195], v[112:115]
	s_setprio 0
	s_add_i32 s59, s52, s3
	v_lshl_add_u64 v[220:221], s[40:41], 0, v[130:131]
	s_mov_b32 m0, s59
	ds_read_b128 v[188:191], v157 offset:16384
	ds_read_b128 v[192:195], v157 offset:17408
	ds_read_b128 v[196:199], v157 offset:18432
	ds_read_b128 v[200:203], v157 offset:19456
	ds_read_b128 v[204:207], v157 offset:20480
	ds_read_b128 v[208:211], v157 offset:21504
	ds_read_b128 v[212:215], v157 offset:22528
	ds_read_b128 v[216:219], v157 offset:23552
	global_load_lds_dwordx4 v130, s[40:41]
	s_add_i32 m0, s59, 0x2000
	s_add_u32 s62, s40, 0x160000
	v_lshl_add_u64 v[222:223], s[40:41], 0, v[134:135]
	s_addc_u32 s63, s41, 0
	s_add_i32 s59, s53, s3
	global_load_lds_dwordx4 v134, s[40:41]
	s_mov_b32 m0, s59
	v_lshl_add_u64 v[226:227], s[42:43], 0, v[132:133]
	global_load_lds_dwordx4 v130, s[62:63]
	s_add_i32 m0, s59, 0x2000
	s_nop 0
	global_load_lds_dwordx4 v134, s[62:63]
	v_lshl_add_u64 v[224:225], s[42:43], 0, v[128:129]
	s_mov_b32 m0, s33
	s_nop 0
	global_load_lds_dwordx4 v128, s[42:43]
	s_mov_b32 m0, s35
	s_nop 0
	global_load_lds_dwordx4 v132, s[42:43]
	s_waitcnt vmcnt(8)
	s_waitcnt lgkmcnt(0)
	s_setprio 1
	s_barrier
	v_mfma_f32_16x16x32_bf16 v[60:63], v[144:147], v[188:191], v[60:63]
	v_mfma_f32_16x16x32_bf16 v[60:63], v[160:163], v[192:195], v[60:63]
	v_mfma_f32_16x16x32_bf16 v[44:47], v[144:147], v[196:199], v[44:47]
	v_mfma_f32_16x16x32_bf16 v[44:47], v[160:163], v[200:203], v[44:47]
	v_mfma_f32_16x16x32_bf16 v[28:31], v[144:147], v[204:207], v[28:31]
	v_mfma_f32_16x16x32_bf16 v[28:31], v[160:163], v[208:211], v[28:31]
	v_mfma_f32_16x16x32_bf16 v[12:15], v[144:147], v[212:215], v[12:15]
	v_mfma_f32_16x16x32_bf16 v[12:15], v[160:163], v[216:219], v[12:15]
	v_mfma_f32_16x16x32_bf16 v[8:11], v[164:167], v[212:215], v[8:11]
	v_mfma_f32_16x16x32_bf16 v[8:11], v[168:171], v[216:219], v[8:11]
	v_mfma_f32_16x16x32_bf16 v[24:27], v[164:167], v[204:207], v[24:27]
	v_mfma_f32_16x16x32_bf16 v[24:27], v[168:171], v[208:211], v[24:27]
	v_mfma_f32_16x16x32_bf16 v[40:43], v[164:167], v[196:199], v[40:43]
	v_mfma_f32_16x16x32_bf16 v[40:43], v[168:171], v[200:203], v[40:43]
	v_mfma_f32_16x16x32_bf16 v[56:59], v[164:167], v[188:191], v[56:59]
	v_mfma_f32_16x16x32_bf16 v[56:59], v[168:171], v[192:195], v[56:59]
	v_mfma_f32_16x16x32_bf16 v[52:55], v[172:175], v[188:191], v[52:55]
	v_mfma_f32_16x16x32_bf16 v[52:55], v[176:179], v[192:195], v[52:55]
	v_mfma_f32_16x16x32_bf16 v[36:39], v[172:175], v[196:199], v[36:39]
	v_mfma_f32_16x16x32_bf16 v[36:39], v[176:179], v[200:203], v[36:39]
	v_mfma_f32_16x16x32_bf16 v[20:23], v[172:175], v[204:207], v[20:23]
	v_mfma_f32_16x16x32_bf16 v[20:23], v[176:179], v[208:211], v[20:23]
	v_mfma_f32_16x16x32_bf16 v[4:7], v[172:175], v[212:215], v[4:7]
	v_mfma_f32_16x16x32_bf16 v[4:7], v[176:179], v[216:219], v[4:7]
	v_mfma_f32_16x16x32_bf16 v[0:3], v[180:183], v[212:215], v[0:3]
	v_mfma_f32_16x16x32_bf16 v[0:3], v[184:187], v[216:219], v[0:3]
	v_mfma_f32_16x16x32_bf16 v[16:19], v[180:183], v[204:207], v[16:19]
	v_mfma_f32_16x16x32_bf16 v[16:19], v[184:187], v[208:211], v[16:19]
	s_setprio 2
	s_barrier
; #define PG8_STAGE(bufoff, gbase, voff) do { _Pragma("unroll") for (int _i = 0; _i < 2; ++_i) \
;         __builtin_amdgcn_global_load_lds((const unsigned*)((const char*)(gbase) + (voff)[_i]), (PG8_LAS unsigned*)(lds + (bufoff) + ldsw + _i * 8192), 16, 0, 0); } while (0)
; #define PG8_LDA(dst, b, h) do { _Pragma("unroll") for (int m = 0; m < 4; ++m) _Pragma("unroll") for (int k = 0; k < 2; ++k) dst[m][k] = *(const PG8_LAS bf16x8*)(lds + PG8_SA(b, h) + aoff + m * 2048 + k * 1024); } while (0)
; #define PG8_LDB(dst, b, h) do { _Pragma("unroll") for (int n = 0; n < 2; ++n) _Pragma("unroll") for (int k = 0; k < 2; ++k) dst[n][k] = *(const PG8_LAS bf16x8*)(lds + PG8_SB(b, h) + boff + n * 2048 + k * 1024); } while (0)
; #define PG8_MMA(ai, bj, At, Bt) do { __builtin_amdgcn_s_setprio(1); _Pragma("unroll") for (int m = 0; m < 4; ++m) _Pragma("unroll") for (int n = 0; n < 2; ++n) _Pragma("unroll") for (int k = 0; k < 2; ++k) \
;         acc[ai][bj][m][n] = __builtin_amdgcn_mfma_f32_16x16x32_bf16(Bt[n][k], At[m][k], acc[ai][bj][m][n], 0, 0, 0); __builtin_amdgcn_s_setprio(0); } while (0)
; #define PG8_WAIT_V(n) asm volatile("s_waitcnt vmcnt(" #n ")" ::: "memory")
; #define PG8_WAIT_L(n) asm volatile("s_waitcnt lgkmcnt(" #n ")" ::: "memory")
; #define PG8_BAR __builtin_amdgcn_s_barrier()
; #define PG8_SCHED __builtin_amdgcn_sched_barrier(0)
; template <class Epi, class Sched, bool ALIGN_EPI = false, bool SP2 = false>
; __device__ __forceinline__ void gemm_phase(PG8_LAS unsigned char* lds, const Gemm g, const Sched& S, const Epi& E) {
;     ...
;             PG8_WAIT_V(8); PG8_WAIT_L(0); PG8_BAR; PG8_MMA(1, 0, At, B0); PG8_MMA(1, 1, At, B1); PG8_BAR; PG8_SCHED;
;             PG8_LDB(B0, 1, 0); PG8_LDB(B1, 1, 1); PG8_SCHED; PG8_LDA(At, 1, 0); PG8_STAGE(PG8_SA(0, 1), a2 + hstep, voffA);
;             PG8_WAIT_V(8); PG8_WAIT_L(0); PG8_BAR; PG8_MMA(0, 0, At, B0); PG8_MMA(0, 1, At, B1); PG8_BAR; PG8_SCHED;
	v_mfma_f32_16x16x32_bf16 v[32:35], v[180:183], v[196:199], v[32:35]
	v_mfma_f32_16x16x32_bf16 v[32:35], v[184:187], v[200:203], v[32:35]
	v_mfma_f32_16x16x32_bf16 v[48:51], v[180:183], v[188:191], v[48:51]
	v_mfma_f32_16x16x32_bf16 v[48:51], v[184:187], v[192:195], v[48:51]
	s_setprio 0
	s_add_i32 s59, 0, 0x18000
	v_add_u32_e32 v159, s59, v153
	s_add_i32 s61, 0, 0x1c000
	ds_read_b128 v[144:147], v159
	ds_read_b128 v[160:163], v159 offset:1024
	ds_read_b128 v[164:167], v159 offset:2048
	ds_read_b128 v[168:171], v159 offset:3072
	v_add_u32_e32 v159, s61, v153
	ds_read_b128 v[172:175], v159
	ds_read_b128 v[176:179], v159 offset:1024
	ds_read_b128 v[180:183], v159 offset:2048
	ds_read_b128 v[184:187], v159 offset:3072
	s_add_u32 s42, s42, 0x160000
	s_addc_u32 s43, s43, 0
	s_mov_b32 m0, s44
	ds_read_b128 v[188:191], v157 offset:32768
	ds_read_b128 v[192:195], v157 offset:33792
	ds_read_b128 v[196:199], v157 offset:34816
	ds_read_b128 v[200:203], v157 offset:35840
	ds_read_b128 v[204:207], v157 offset:36864
	ds_read_b128 v[208:211], v157 offset:37888
	ds_read_b128 v[212:215], v157 offset:38912
	ds_read_b128 v[216:219], v157 offset:39936
	global_load_lds_dwordx4 v128, s[42:43]
	s_mov_b32 m0, s45
	s_nop 0
	global_load_lds_dwordx4 v132, s[42:43]
	s_waitcnt vmcnt(8)
	s_waitcnt lgkmcnt(0)
	s_setprio 1
	s_barrier
	v_mfma_f32_16x16x32_bf16 v[124:127], v[144:147], v[188:191], v[124:127]
	v_mfma_f32_16x16x32_bf16 v[124:127], v[160:163], v[192:195], v[124:127]
	v_mfma_f32_16x16x32_bf16 v[108:111], v[144:147], v[196:199], v[108:111]
	v_mfma_f32_16x16x32_bf16 v[108:111], v[160:163], v[200:203], v[108:111]
	v_mfma_f32_16x16x32_bf16 v[92:95], v[144:147], v[204:207], v[92:95]
	v_mfma_f32_16x16x32_bf16 v[92:95], v[160:163], v[208:211], v[92:95]
	v_mfma_f32_16x16x32_bf16 v[76:79], v[144:147], v[212:215], v[76:79]
	v_mfma_f32_16x16x32_bf16 v[76:79], v[160:163], v[216:219], v[76:79]
	v_mfma_f32_16x16x32_bf16 v[72:75], v[164:167], v[212:215], v[72:75]
	v_mfma_f32_16x16x32_bf16 v[72:75], v[168:171], v[216:219], v[72:75]
	v_mfma_f32_16x16x32_bf16 v[88:91], v[164:167], v[204:207], v[88:91]
	v_mfma_f32_16x16x32_bf16 v[88:91], v[168:171], v[208:211], v[88:91]
	v_mfma_f32_16x16x32_bf16 v[104:107], v[164:167], v[196:199], v[104:107]
	v_mfma_f32_16x16x32_bf16 v[104:107], v[168:171], v[200:203], v[104:107]
	v_mfma_f32_16x16x32_bf16 v[120:123], v[164:167], v[188:191], v[120:123]
	v_mfma_f32_16x16x32_bf16 v[120:123], v[168:171], v[192:195], v[120:123]
	v_mfma_f32_16x16x32_bf16 v[116:119], v[172:175], v[188:191], v[116:119]
	v_mfma_f32_16x16x32_bf16 v[116:119], v[176:179], v[192:195], v[116:119]
	v_mfma_f32_16x16x32_bf16 v[100:103], v[172:175], v[196:199], v[100:103]
	v_mfma_f32_16x16x32_bf16 v[100:103], v[176:179], v[200:203], v[100:103]
	v_mfma_f32_16x16x32_bf16 v[84:87], v[172:175], v[204:207], v[84:87]
	v_mfma_f32_16x16x32_bf16 v[84:87], v[176:179], v[208:211], v[84:87]
	v_mfma_f32_16x16x32_bf16 v[68:71], v[172:175], v[212:215], v[68:71]
	v_mfma_f32_16x16x32_bf16 v[68:71], v[176:179], v[216:219], v[68:71]
	v_mfma_f32_16x16x32_bf16 v[64:67], v[180:183], v[212:215], v[64:67]
	v_mfma_f32_16x16x32_bf16 v[64:67], v[184:187], v[216:219], v[64:67]
	v_mfma_f32_16x16x32_bf16 v[80:83], v[180:183], v[204:207], v[80:83]
	v_mfma_f32_16x16x32_bf16 v[80:83], v[184:187], v[208:211], v[80:83]
	s_setprio 2
	s_barrier
; #define PG8_STAGE(bufoff, gbase, voff) do { _Pragma("unroll") for (int _i = 0; _i < 2; ++_i) \
;         __builtin_amdgcn_global_load_lds((const unsigned*)((const char*)(gbase) + (voff)[_i]), (PG8_LAS unsigned*)(lds + (bufoff) + ldsw + _i * 8192), 16, 0, 0); } while (0)
; #define PG8_LDA(dst, b, h) do { _Pragma("unroll") for (int m = 0; m < 4; ++m) _Pragma("unroll") for (int k = 0; k < 2; ++k) dst[m][k] = *(const PG8_LAS bf16x8*)(lds + PG8_SA(b, h) + aoff + m * 2048 + k * 1024); } while (0)
; #define PG8_MMA(ai, bj, At, Bt) do { __builtin_amdgcn_s_setprio(1); _Pragma("unroll") for (int m = 0; m < 4; ++m) _Pragma("unroll") for (int n = 0; n < 2; ++n) _Pragma("unroll") for (int k = 0; k < 2; ++k) \
;         acc[ai][bj][m][n] = __builtin_amdgcn_mfma_f32_16x16x32_bf16(Bt[n][k], At[m][k], acc[ai][bj][m][n], 0, 0, 0); __builtin_amdgcn_s_setprio(0); } while (0)
; #define PG8_WAIT_V(n) asm volatile("s_waitcnt vmcnt(" #n ")" ::: "memory")
; #define PG8_WAIT_L(n) asm volatile("s_waitcnt lgkmcnt(" #n ")" ::: "memory")
; #define PG8_BAR __builtin_amdgcn_s_barrier()
; #define PG8_SCHED __builtin_amdgcn_sched_barrier(0)
; template <class Epi, class Sched, bool ALIGN_EPI = false, bool SP2 = false>
; __device__ __forceinline__ void gemm_phase(PG8_LAS unsigned char* lds, const Gemm g, const Sched& S, const Epi& E) {
;     ...
;             PG8_WAIT_V(8); PG8_WAIT_L(0); PG8_BAR; PG8_MMA(0, 0, At, B0); PG8_MMA(0, 1, At, B1); PG8_BAR; PG8_SCHED;
;             PG8_LDA(At, 1, 1); PG8_STAGE(PG8_SB(1, 0), b3, voffB); PG8_STAGE(PG8_SB(1, 1), b3 + hstep, voffB); PG8_STAGE(PG8_SA(1, 0), a3, voffA);
;             PG8_WAIT_V(8); PG8_WAIT_L(0); PG8_BAR; PG8_MMA(1, 0, At, B0); PG8_MMA(1, 1, At, B1); PG8_BAR; PG8_SCHED;
;     ...
;         if constexpr (ALIGN_EPI) { if (wr == 0) PG8_BAR; }
	v_mfma_f32_16x16x32_bf16 v[96:99], v[180:183], v[196:199], v[96:99]
	v_mfma_f32_16x16x32_bf16 v[96:99], v[184:187], v[200:203], v[96:99]
	v_mfma_f32_16x16x32_bf16 v[112:115], v[180:183], v[188:191], v[112:115]
	v_mfma_f32_16x16x32_bf16 v[112:115], v[184:187], v[192:195], v[112:115]
	s_setprio 0
	s_add_i32 s42, s59, s3
	v_lshl_add_u64 v[220:221], v[220:221], 0, s[16:17]
	s_mov_b32 m0, s42
	ds_read_b128 v[188:191], v157 offset:49152
	ds_read_b128 v[192:195], v157 offset:50176
	ds_read_b128 v[196:199], v157 offset:51200
	ds_read_b128 v[200:203], v157 offset:52224
	ds_read_b128 v[204:207], v157 offset:53248
	ds_read_b128 v[208:211], v157 offset:54272
	ds_read_b128 v[212:215], v157 offset:55296
	ds_read_b128 v[216:219], v157 offset:56320
	global_load_lds_dwordx4 v[220:221], off
	s_add_i32 m0, s42, 0x2000
	s_add_u32 s40, s40, 0x160080
	v_lshl_add_u64 v[220:221], v[222:223], 0, s[16:17]
	s_addc_u32 s41, s41, 0
	s_add_i32 s42, s61, s3
	global_load_lds_dwordx4 v[220:221], off
	s_mov_b32 m0, s42
	s_nop 0
	global_load_lds_dwordx4 v130, s[40:41]
	s_add_i32 m0, s42, 0x2000
	s_nop 0
	global_load_lds_dwordx4 v134, s[40:41]
	v_lshl_add_u64 v[220:221], v[224:225], 0, s[16:17]
	s_mov_b32 m0, s49
	s_nop 0
	global_load_lds_dwordx4 v[220:221], off
	v_lshl_add_u64 v[220:221], v[226:227], 0, s[16:17]
	s_mov_b32 m0, s50
	s_nop 0
	global_load_lds_dwordx4 v[220:221], off
	s_waitcnt vmcnt(8)
	s_waitcnt lgkmcnt(0)
	s_setprio 1
	s_barrier
	v_mfma_f32_16x16x32_bf16 v[60:63], v[144:147], v[188:191], v[60:63]
	v_mfma_f32_16x16x32_bf16 v[60:63], v[160:163], v[192:195], v[60:63]
	v_mfma_f32_16x16x32_bf16 v[44:47], v[144:147], v[196:199], v[44:47]
	v_mfma_f32_16x16x32_bf16 v[44:47], v[160:163], v[200:203], v[44:47]
	v_mfma_f32_16x16x32_bf16 v[28:31], v[144:147], v[204:207], v[28:31]
	v_mfma_f32_16x16x32_bf16 v[28:31], v[160:163], v[208:211], v[28:31]
	v_mfma_f32_16x16x32_bf16 v[12:15], v[144:147], v[212:215], v[12:15]
	v_mfma_f32_16x16x32_bf16 v[12:15], v[160:163], v[216:219], v[12:15]
	v_mfma_f32_16x16x32_bf16 v[8:11], v[164:167], v[212:215], v[8:11]
	v_mfma_f32_16x16x32_bf16 v[8:11], v[168:171], v[216:219], v[8:11]
	v_mfma_f32_16x16x32_bf16 v[24:27], v[164:167], v[204:207], v[24:27]
	v_mfma_f32_16x16x32_bf16 v[24:27], v[168:171], v[208:211], v[24:27]
	v_mfma_f32_16x16x32_bf16 v[40:43], v[164:167], v[196:199], v[40:43]
	v_mfma_f32_16x16x32_bf16 v[40:43], v[168:171], v[200:203], v[40:43]
	v_mfma_f32_16x16x32_bf16 v[56:59], v[164:167], v[188:191], v[56:59]
	v_mfma_f32_16x16x32_bf16 v[56:59], v[168:171], v[192:195], v[56:59]
	v_mfma_f32_16x16x32_bf16 v[52:55], v[172:175], v[188:191], v[52:55]
	v_mfma_f32_16x16x32_bf16 v[52:55], v[176:179], v[192:195], v[52:55]
	v_mfma_f32_16x16x32_bf16 v[36:39], v[172:175], v[196:199], v[36:39]
	v_mfma_f32_16x16x32_bf16 v[36:39], v[176:179], v[200:203], v[36:39]
	v_mfma_f32_16x16x32_bf16 v[20:23], v[172:175], v[204:207], v[20:23]
	v_mfma_f32_16x16x32_bf16 v[20:23], v[176:179], v[208:211], v[20:23]
	v_mfma_f32_16x16x32_bf16 v[4:7], v[172:175], v[212:215], v[4:7]
	v_mfma_f32_16x16x32_bf16 v[4:7], v[176:179], v[216:219], v[4:7]
	v_mfma_f32_16x16x32_bf16 v[0:3], v[180:183], v[212:215], v[0:3]
	v_mfma_f32_16x16x32_bf16 v[0:3], v[184:187], v[216:219], v[0:3]
	v_mfma_f32_16x16x32_bf16 v[16:19], v[180:183], v[204:207], v[16:19]
	v_mfma_f32_16x16x32_bf16 v[16:19], v[184:187], v[208:211], v[16:19]
	s_setprio 2
	s_barrier
	v_mfma_f32_16x16x32_bf16 v[32:35], v[180:183], v[196:199], v[32:35]
	v_mfma_f32_16x16x32_bf16 v[32:35], v[184:187], v[200:203], v[32:35]
	v_mfma_f32_16x16x32_bf16 v[48:51], v[180:183], v[188:191], v[48:51]
	v_mfma_f32_16x16x32_bf16 v[48:51], v[184:187], v[192:195], v[48:51]
	s_setprio 0
	s_add_i32 s58, s58, 2
	s_add_u32 s38, s38, 0x100
	s_addc_u32 s39, s39, 0
	s_add_u32 s11, s11, 0x100
	s_addc_u32 s57, s57, 0
	s_cmpk_gt_u32 s58, 0x55
	s_cbranch_scc0 .LBB0_779
	s_and_b64 vcc, exec, s[20:21]
	s_cbranch_vccz .LBB0_782
	s_barrier
